# v10: K-loop loop-edge edit: back-edge pointer SALU moved above closing barrier, head select SALU sunk below ds_read burst
# speedup vs baseline: 1.0014x; 1.0014x over previous
.LBB0_271:
	s_add_i32 s54, 0, 0x10000
	v_add_u32_e32 v154, s54, v141
	s_add_i32 s56, 0, 0x14000
	ds_read_b128 v[146:149], v154
	ds_read_b128 v[150:153], v154 offset:1024
	ds_read_b128 v[162:165], v154 offset:2048
	ds_read_b128 v[166:169], v154 offset:3072
	v_add_u32_e32 v154, s56, v141
	ds_read_b128 v[170:173], v154
	ds_read_b128 v[186:189], v154 offset:1024
	ds_read_b128 v[190:193], v154 offset:2048
	ds_read_b128 v[194:197], v154 offset:3072
	s_add_u32 s26, s14, 0xfffc0080
	s_addc_u32 s27, s15, -1
	s_cmp_eq_u32 s53, 12
	s_cselect_b32 s29, s21, s27
	s_cselect_b32 s28, s49, s26
	s_cselect_b32 s27, s19, s52
	s_cselect_b32 s26, s50, s51
	v_lshl_add_u64 v[154:155], s[14:15], 0, v[136:137]
	s_add_i32 m0, s37, 0xc000
	ds_read_b128 v[198:201], v145
	ds_read_b128 v[202:205], v145 offset:1024
	ds_read_b128 v[206:209], v145 offset:2048
	ds_read_b128 v[210:213], v145 offset:3072
	ds_read_b128 v[214:217], v145 offset:4096
	ds_read_b128 v[218:221], v145 offset:5120
	ds_read_b128 v[222:225], v145 offset:6144
	ds_read_b128 v[226:229], v145 offset:7168
	global_load_lds_dwordx4 v[154:155], off
	v_lshl_add_u64 v[154:155], s[14:15], 0, v[138:139]
	s_add_i32 m0, s37, 0xe000
	s_nop 0
	global_load_lds_dwordx4 v[154:155], off
	s_setprio 0
	s_waitcnt vmcnt(8)
	s_waitcnt lgkmcnt(0)
	s_barrier
	s_setprio 1
	v_mfma_f32_16x16x32_bf16 v[126:129], v[146:149], v[198:201], v[126:129]
	v_mfma_f32_16x16x32_bf16 v[122:125], v[162:165], v[198:201], v[122:125]
	v_mfma_f32_16x16x32_bf16 v[110:113], v[146:149], v[206:209], v[110:113]
	v_mfma_f32_16x16x32_bf16 v[106:109], v[162:165], v[206:209], v[106:109]
	v_mfma_f32_16x16x32_bf16 v[92:95], v[146:149], v[214:217], v[92:95]
	v_mfma_f32_16x16x32_bf16 v[88:91], v[162:165], v[214:217], v[88:91]
	v_mfma_f32_16x16x32_bf16 v[76:79], v[146:149], v[222:225], v[76:79]
	v_mfma_f32_16x16x32_bf16 v[72:75], v[162:165], v[222:225], v[72:75]
	v_mfma_f32_16x16x32_bf16 v[126:129], v[150:153], v[202:205], v[126:129]
	v_mfma_f32_16x16x32_bf16 v[122:125], v[166:169], v[202:205], v[122:125]
	v_mfma_f32_16x16x32_bf16 v[110:113], v[150:153], v[210:213], v[110:113]
	v_mfma_f32_16x16x32_bf16 v[106:109], v[166:169], v[210:213], v[106:109]
	v_mfma_f32_16x16x32_bf16 v[92:95], v[150:153], v[218:221], v[92:95]
	v_mfma_f32_16x16x32_bf16 v[88:91], v[166:169], v[218:221], v[88:91]
	v_mfma_f32_16x16x32_bf16 v[76:79], v[150:153], v[226:229], v[76:79]
	v_mfma_f32_16x16x32_bf16 v[72:75], v[166:169], v[226:229], v[72:75]
	s_setprio 0
	s_setprio 1
	v_mfma_f32_16x16x32_bf16 v[118:121], v[170:173], v[198:201], v[118:121]
	v_mfma_f32_16x16x32_bf16 v[114:117], v[190:193], v[198:201], v[114:117]
	v_mfma_f32_16x16x32_bf16 v[102:105], v[170:173], v[206:209], v[102:105]
	v_mfma_f32_16x16x32_bf16 v[98:101], v[190:193], v[206:209], v[98:101]
	v_mfma_f32_16x16x32_bf16 v[84:87], v[170:173], v[214:217], v[84:87]
	v_mfma_f32_16x16x32_bf16 v[80:83], v[190:193], v[214:217], v[80:83]
	v_mfma_f32_16x16x32_bf16 v[68:71], v[170:173], v[222:225], v[68:71]
	v_mfma_f32_16x16x32_bf16 v[64:67], v[190:193], v[222:225], v[64:67]
	v_mfma_f32_16x16x32_bf16 v[118:121], v[186:189], v[202:205], v[118:121]
	v_mfma_f32_16x16x32_bf16 v[114:117], v[194:197], v[202:205], v[114:117]
	v_mfma_f32_16x16x32_bf16 v[102:105], v[186:189], v[210:213], v[102:105]
	v_mfma_f32_16x16x32_bf16 v[98:101], v[194:197], v[210:213], v[98:101]
	v_mfma_f32_16x16x32_bf16 v[84:87], v[186:189], v[218:221], v[84:87]
	v_mfma_f32_16x16x32_bf16 v[80:83], v[194:197], v[218:221], v[80:83]
	v_mfma_f32_16x16x32_bf16 v[68:71], v[186:189], v[226:229], v[68:71]
	v_mfma_f32_16x16x32_bf16 v[64:67], v[194:197], v[226:229], v[64:67]
	s_setprio 0
	s_barrier
	s_setprio 2
	s_add_i32 s54, s54, s36
	v_lshl_add_u64 v[154:155], s[26:27], 0, v[96:97]
	s_mov_b32 m0, s54
	ds_read_b128 v[198:201], v145 offset:16384
	ds_read_b128 v[202:205], v145 offset:17408
	ds_read_b128 v[206:209], v145 offset:18432
	ds_read_b128 v[210:213], v145 offset:19456
	ds_read_b128 v[214:217], v145 offset:20480
	ds_read_b128 v[218:221], v145 offset:21504
	ds_read_b128 v[222:225], v145 offset:22528
	ds_read_b128 v[226:229], v145 offset:23552
	global_load_lds_dwordx4 v[154:155], off
	s_add_i32 m0, s54, 0x2000
	s_add_u32 s54, s26, 0x40000
	v_lshl_add_u64 v[156:157], s[26:27], 0, v[130:131]
	s_addc_u32 s55, s27, 0
	s_add_i32 s56, s56, s36
	global_load_lds_dwordx4 v[156:157], off
	v_lshl_add_u64 v[158:159], s[54:55], 0, v[96:97]
	s_mov_b32 m0, s56
	v_lshl_add_u64 v[182:183], s[28:29], 0, v[132:133]
	global_load_lds_dwordx4 v[158:159], off
	v_lshl_add_u64 v[158:159], s[54:55], 0, v[130:131]
	s_add_i32 m0, s56, 0x2000
	s_nop 0
	global_load_lds_dwordx4 v[158:159], off
	v_lshl_add_u64 v[158:159], s[28:29], 0, v[134:135]
	s_mov_b32 m0, s37
	s_nop 0
	global_load_lds_dwordx4 v[158:159], off
	s_mov_b32 m0, s38
	s_nop 0
	global_load_lds_dwordx4 v[182:183], off
	s_setprio 0
	s_waitcnt vmcnt(8)
	s_waitcnt lgkmcnt(0)
	s_barrier
	s_setprio 1
	v_mfma_f32_16x16x32_bf16 v[60:63], v[146:149], v[198:201], v[60:63]
	v_mfma_f32_16x16x32_bf16 v[56:59], v[162:165], v[198:201], v[56:59]
	v_mfma_f32_16x16x32_bf16 v[44:47], v[146:149], v[206:209], v[44:47]
	v_mfma_f32_16x16x32_bf16 v[40:43], v[162:165], v[206:209], v[40:43]
	v_mfma_f32_16x16x32_bf16 v[28:31], v[146:149], v[214:217], v[28:31]
	v_mfma_f32_16x16x32_bf16 v[24:27], v[162:165], v[214:217], v[24:27]
	v_mfma_f32_16x16x32_bf16 v[12:15], v[146:149], v[222:225], v[12:15]
	v_mfma_f32_16x16x32_bf16 v[4:7], v[162:165], v[222:225], v[4:7]
	v_mfma_f32_16x16x32_bf16 v[60:63], v[150:153], v[202:205], v[60:63]
	v_mfma_f32_16x16x32_bf16 v[56:59], v[166:169], v[202:205], v[56:59]
	v_mfma_f32_16x16x32_bf16 v[44:47], v[150:153], v[210:213], v[44:47]
	v_mfma_f32_16x16x32_bf16 v[40:43], v[166:169], v[210:213], v[40:43]
	v_mfma_f32_16x16x32_bf16 v[28:31], v[150:153], v[218:221], v[28:31]
	v_mfma_f32_16x16x32_bf16 v[24:27], v[166:169], v[218:221], v[24:27]
	v_mfma_f32_16x16x32_bf16 v[12:15], v[150:153], v[226:229], v[12:15]
	v_mfma_f32_16x16x32_bf16 v[4:7], v[166:169], v[226:229], v[4:7]
	s_setprio 0
	s_setprio 1
	v_mfma_f32_16x16x32_bf16 v[52:55], v[170:173], v[198:201], v[52:55]
	v_mfma_f32_16x16x32_bf16 v[48:51], v[190:193], v[198:201], v[48:51]
	v_mfma_f32_16x16x32_bf16 v[36:39], v[170:173], v[206:209], v[36:39]
	v_mfma_f32_16x16x32_bf16 v[32:35], v[190:193], v[206:209], v[32:35]
	v_mfma_f32_16x16x32_bf16 v[20:23], v[170:173], v[214:217], v[20:23]
	v_mfma_f32_16x16x32_bf16 v[16:19], v[190:193], v[214:217], v[16:19]
	v_mfma_f32_16x16x32_bf16 v[8:11], v[170:173], v[222:225], v[8:11]
	v_mfma_f32_16x16x32_bf16 v[0:3], v[190:193], v[222:225], v[0:3]
	v_mfma_f32_16x16x32_bf16 v[52:55], v[186:189], v[202:205], v[52:55]
	v_mfma_f32_16x16x32_bf16 v[48:51], v[194:197], v[202:205], v[48:51]
	v_mfma_f32_16x16x32_bf16 v[36:39], v[186:189], v[210:213], v[36:39]
	v_mfma_f32_16x16x32_bf16 v[32:35], v[194:197], v[210:213], v[32:35]
	v_mfma_f32_16x16x32_bf16 v[20:23], v[186:189], v[218:221], v[20:23]
	v_mfma_f32_16x16x32_bf16 v[16:19], v[194:197], v[218:221], v[16:19]
	v_mfma_f32_16x16x32_bf16 v[8:11], v[186:189], v[226:229], v[8:11]
	v_mfma_f32_16x16x32_bf16 v[0:3], v[194:197], v[226:229], v[0:3]
	s_setprio 0
	s_barrier
	s_setprio 2
	s_add_i32 s54, 0, 0x18000
	s_add_i32 s55, 0, 0x1c000
	v_add_u32_e32 v166, s54, v141
	v_add_u32_e32 v184, s55, v141
	ds_read_b128 v[146:149], v166
	ds_read_b128 v[150:153], v166 offset:1024
	ds_read_b128 v[162:165], v166 offset:2048
	ds_read_b128 v[166:169], v166 offset:3072
	ds_read_b128 v[170:173], v184
	ds_read_b128 v[186:189], v184 offset:1024
	ds_read_b128 v[190:193], v184 offset:2048
	ds_read_b128 v[194:197], v184 offset:3072
	s_add_u32 s28, s28, 0x40000
	s_addc_u32 s29, s29, 0
	s_mov_b32 m0, s39
	v_lshl_add_u64 v[184:185], s[28:29], 0, v[134:135]
	ds_read_b128 v[198:201], v145 offset:32768
	ds_read_b128 v[202:205], v145 offset:33792
	ds_read_b128 v[206:209], v145 offset:34816
	ds_read_b128 v[210:213], v145 offset:35840
	ds_read_b128 v[214:217], v145 offset:36864
	ds_read_b128 v[218:221], v145 offset:37888
	ds_read_b128 v[222:225], v145 offset:38912
	ds_read_b128 v[226:229], v145 offset:39936
	global_load_lds_dwordx4 v[184:185], off
	v_lshl_add_u64 v[184:185], s[28:29], 0, v[132:133]
	s_mov_b32 m0, s40
	s_nop 0
	global_load_lds_dwordx4 v[184:185], off
	s_setprio 0
	s_waitcnt vmcnt(8)
	s_waitcnt lgkmcnt(0)
	s_barrier
	s_setprio 1
	v_mfma_f32_16x16x32_bf16 v[126:129], v[146:149], v[198:201], v[126:129]
	v_mfma_f32_16x16x32_bf16 v[122:125], v[162:165], v[198:201], v[122:125]
	v_mfma_f32_16x16x32_bf16 v[110:113], v[146:149], v[206:209], v[110:113]
	v_mfma_f32_16x16x32_bf16 v[106:109], v[162:165], v[206:209], v[106:109]
	v_mfma_f32_16x16x32_bf16 v[92:95], v[146:149], v[214:217], v[92:95]
	v_mfma_f32_16x16x32_bf16 v[88:91], v[162:165], v[214:217], v[88:91]
	v_mfma_f32_16x16x32_bf16 v[76:79], v[146:149], v[222:225], v[76:79]
	v_mfma_f32_16x16x32_bf16 v[72:75], v[162:165], v[222:225], v[72:75]
	v_mfma_f32_16x16x32_bf16 v[126:129], v[150:153], v[202:205], v[126:129]
	v_mfma_f32_16x16x32_bf16 v[122:125], v[166:169], v[202:205], v[122:125]
	v_mfma_f32_16x16x32_bf16 v[110:113], v[150:153], v[210:213], v[110:113]
	v_mfma_f32_16x16x32_bf16 v[106:109], v[166:169], v[210:213], v[106:109]
	v_mfma_f32_16x16x32_bf16 v[92:95], v[150:153], v[218:221], v[92:95]
	v_mfma_f32_16x16x32_bf16 v[88:91], v[166:169], v[218:221], v[88:91]
	v_mfma_f32_16x16x32_bf16 v[76:79], v[150:153], v[226:229], v[76:79]
	v_mfma_f32_16x16x32_bf16 v[72:75], v[166:169], v[226:229], v[72:75]
	s_setprio 0
	s_setprio 1
	v_mfma_f32_16x16x32_bf16 v[118:121], v[170:173], v[198:201], v[118:121]
	v_mfma_f32_16x16x32_bf16 v[114:117], v[190:193], v[198:201], v[114:117]
	v_mfma_f32_16x16x32_bf16 v[102:105], v[170:173], v[206:209], v[102:105]
	v_mfma_f32_16x16x32_bf16 v[98:101], v[190:193], v[206:209], v[98:101]
	v_mfma_f32_16x16x32_bf16 v[84:87], v[170:173], v[214:217], v[84:87]
	v_mfma_f32_16x16x32_bf16 v[80:83], v[190:193], v[214:217], v[80:83]
	v_mfma_f32_16x16x32_bf16 v[68:71], v[170:173], v[222:225], v[68:71]
	v_mfma_f32_16x16x32_bf16 v[64:67], v[190:193], v[222:225], v[64:67]
	v_mfma_f32_16x16x32_bf16 v[118:121], v[186:189], v[202:205], v[118:121]
	v_mfma_f32_16x16x32_bf16 v[114:117], v[194:197], v[202:205], v[114:117]
	v_mfma_f32_16x16x32_bf16 v[102:105], v[186:189], v[210:213], v[102:105]
	v_mfma_f32_16x16x32_bf16 v[98:101], v[194:197], v[210:213], v[98:101]
	v_mfma_f32_16x16x32_bf16 v[84:87], v[186:189], v[218:221], v[84:87]
	v_mfma_f32_16x16x32_bf16 v[80:83], v[194:197], v[218:221], v[80:83]
	v_mfma_f32_16x16x32_bf16 v[68:71], v[186:189], v[226:229], v[68:71]
	v_mfma_f32_16x16x32_bf16 v[64:67], v[194:197], v[226:229], v[64:67]
	s_setprio 0
	s_barrier
	s_setprio 2
	s_add_i32 s28, s54, s36
	v_lshl_add_u64 v[154:155], v[154:155], 0, s[16:17]
	s_mov_b32 m0, s28
	ds_read_b128 v[198:201], v145 offset:49152
	ds_read_b128 v[202:205], v145 offset:50176
	ds_read_b128 v[206:209], v145 offset:51200
	ds_read_b128 v[210:213], v145 offset:52224
	ds_read_b128 v[214:217], v145 offset:53248
	ds_read_b128 v[218:221], v145 offset:54272
	ds_read_b128 v[222:225], v145 offset:55296
	ds_read_b128 v[226:229], v145 offset:56320
	global_load_lds_dwordx4 v[154:155], off
	s_add_i32 m0, s28, 0x2000
	s_add_u32 s26, s26, 0x40080
	v_lshl_add_u64 v[154:155], v[156:157], 0, s[16:17]
	s_addc_u32 s27, s27, 0
	s_add_i32 s28, s55, s36
	global_load_lds_dwordx4 v[154:155], off
	v_lshl_add_u64 v[154:155], s[26:27], 0, v[96:97]
	s_mov_b32 m0, s28
	s_nop 0
	global_load_lds_dwordx4 v[154:155], off
	v_lshl_add_u64 v[154:155], s[26:27], 0, v[130:131]
	s_add_i32 m0, s28, 0x2000
	s_nop 0
	global_load_lds_dwordx4 v[154:155], off
	v_lshl_add_u64 v[154:155], v[158:159], 0, s[16:17]
	s_mov_b32 m0, s41
	s_nop 0
	global_load_lds_dwordx4 v[154:155], off
	v_lshl_add_u64 v[154:155], v[182:183], 0, s[16:17]
	s_mov_b32 m0, s42
	s_nop 0
	global_load_lds_dwordx4 v[154:155], off
	s_setprio 0
	s_waitcnt vmcnt(8)
	s_waitcnt lgkmcnt(0)
	s_barrier
	s_setprio 1
	v_mfma_f32_16x16x32_bf16 v[60:63], v[146:149], v[198:201], v[60:63]
	v_mfma_f32_16x16x32_bf16 v[56:59], v[162:165], v[198:201], v[56:59]
	v_mfma_f32_16x16x32_bf16 v[44:47], v[146:149], v[206:209], v[44:47]
	v_mfma_f32_16x16x32_bf16 v[40:43], v[162:165], v[206:209], v[40:43]
	v_mfma_f32_16x16x32_bf16 v[28:31], v[146:149], v[214:217], v[28:31]
	v_mfma_f32_16x16x32_bf16 v[24:27], v[162:165], v[214:217], v[24:27]
	v_mfma_f32_16x16x32_bf16 v[12:15], v[146:149], v[222:225], v[12:15]
	v_mfma_f32_16x16x32_bf16 v[4:7], v[162:165], v[222:225], v[4:7]
	v_mfma_f32_16x16x32_bf16 v[60:63], v[150:153], v[202:205], v[60:63]
	v_mfma_f32_16x16x32_bf16 v[56:59], v[166:169], v[202:205], v[56:59]
	v_mfma_f32_16x16x32_bf16 v[44:47], v[150:153], v[210:213], v[44:47]
	v_mfma_f32_16x16x32_bf16 v[40:43], v[166:169], v[210:213], v[40:43]
	v_mfma_f32_16x16x32_bf16 v[28:31], v[150:153], v[218:221], v[28:31]
	v_mfma_f32_16x16x32_bf16 v[24:27], v[166:169], v[218:221], v[24:27]
	v_mfma_f32_16x16x32_bf16 v[12:15], v[150:153], v[226:229], v[12:15]
	v_mfma_f32_16x16x32_bf16 v[4:7], v[166:169], v[226:229], v[4:7]
	s_setprio 0
	s_setprio 1
	v_mfma_f32_16x16x32_bf16 v[52:55], v[170:173], v[198:201], v[52:55]
	v_mfma_f32_16x16x32_bf16 v[48:51], v[190:193], v[198:201], v[48:51]
	v_mfma_f32_16x16x32_bf16 v[36:39], v[170:173], v[206:209], v[36:39]
	v_mfma_f32_16x16x32_bf16 v[32:35], v[190:193], v[206:209], v[32:35]
	v_mfma_f32_16x16x32_bf16 v[20:23], v[170:173], v[214:217], v[20:23]
	v_mfma_f32_16x16x32_bf16 v[16:19], v[190:193], v[214:217], v[16:19]
	v_mfma_f32_16x16x32_bf16 v[8:11], v[170:173], v[222:225], v[8:11]
	v_mfma_f32_16x16x32_bf16 v[0:3], v[190:193], v[222:225], v[0:3]
	v_mfma_f32_16x16x32_bf16 v[52:55], v[186:189], v[202:205], v[52:55]
	v_mfma_f32_16x16x32_bf16 v[48:51], v[194:197], v[202:205], v[48:51]
	v_mfma_f32_16x16x32_bf16 v[36:39], v[186:189], v[210:213], v[36:39]
	v_mfma_f32_16x16x32_bf16 v[32:35], v[194:197], v[210:213], v[32:35]
	v_mfma_f32_16x16x32_bf16 v[20:23], v[186:189], v[218:221], v[20:23]
	v_mfma_f32_16x16x32_bf16 v[16:19], v[194:197], v[218:221], v[16:19]
	v_mfma_f32_16x16x32_bf16 v[8:11], v[186:189], v[226:229], v[8:11]
	v_mfma_f32_16x16x32_bf16 v[0:3], v[194:197], v[226:229], v[0:3]
	s_add_i32 s53, s53, 2
	s_add_u32 s14, s14, 0x100
	s_addc_u32 s15, s15, 0
	s_add_u32 s51, s51, 0x100
	s_addc_u32 s52, s52, 0
	s_setprio 0
	s_barrier
	s_setprio 2
	s_cmp_gt_u32 s53, 13
	s_cbranch_scc0 .LBB0_271
	s_and_b64 vcc, exec, s[12:13]
	s_cbranch_vccz .LBB0_274
	s_barrier

.LBB0_361:
	s_add_i32 s62, 0, 0x10000
	v_add_u32_e32 v96, s62, v151
	s_add_i32 s64, 0, 0x14000
	ds_read_b128 v[164:167], v96
	ds_read_b128 v[168:171], v96 offset:1024
	ds_read_b128 v[186:189], v96 offset:2048
	ds_read_b128 v[190:193], v96 offset:3072
	v_add_u32_e32 v96, s64, v151
	ds_read_b128 v[194:197], v96
	ds_read_b128 v[198:201], v96 offset:1024
	ds_read_b128 v[202:205], v96 offset:2048
	ds_read_b128 v[206:209], v96 offset:3072
	s_add_u32 s34, s30, 0xfffc0080
	s_addc_u32 s35, s31, -1
	s_cmp_eq_u32 s61, 12
	s_cselect_b32 s37, s25, s35
	s_cselect_b32 s36, s57, s34
	s_cselect_b32 s35, s15, s60
	s_cselect_b32 s34, s58, s59
	v_lshl_add_u64 v[154:155], s[30:31], 0, v[146:147]
	s_add_i32 m0, s43, 0xc000
	ds_read_b128 v[210:213], v162
	ds_read_b128 v[214:217], v162 offset:1024
	ds_read_b128 v[218:221], v162 offset:2048
	ds_read_b128 v[222:225], v162 offset:3072
	ds_read_b128 v[226:229], v162 offset:4096
	ds_read_b128 v[230:233], v162 offset:5120
	ds_read_b128 v[242:245], v162 offset:6144
	ds_read_b128 v[246:249], v162 offset:7168
	global_load_lds_dwordx4 v[154:155], off
	v_lshl_add_u64 v[154:155], s[30:31], 0, v[148:149]
	s_add_i32 m0, s43, 0xe000
	s_nop 0
	global_load_lds_dwordx4 v[154:155], off
	s_setprio 0
	s_waitcnt vmcnt(8)
	s_waitcnt lgkmcnt(0)
	s_barrier
	s_setprio 1
	v_mfma_f32_16x16x32_bf16 v[126:129], v[164:167], v[210:213], v[126:129]
	v_mfma_f32_16x16x32_bf16 v[122:125], v[186:189], v[210:213], v[122:125]
	v_mfma_f32_16x16x32_bf16 v[118:121], v[164:167], v[218:221], v[118:121]
	v_mfma_f32_16x16x32_bf16 v[114:117], v[186:189], v[218:221], v[114:117]
	v_mfma_f32_16x16x32_bf16 v[110:113], v[164:167], v[226:229], v[110:113]
	v_mfma_f32_16x16x32_bf16 v[106:109], v[186:189], v[226:229], v[106:109]
	v_mfma_f32_16x16x32_bf16 v[102:105], v[164:167], v[242:245], v[102:105]
	v_mfma_f32_16x16x32_bf16 v[98:101], v[186:189], v[242:245], v[98:101]
	v_mfma_f32_16x16x32_bf16 v[126:129], v[168:171], v[214:217], v[126:129]
	v_mfma_f32_16x16x32_bf16 v[122:125], v[190:193], v[214:217], v[122:125]
	v_mfma_f32_16x16x32_bf16 v[118:121], v[168:171], v[222:225], v[118:121]
	v_mfma_f32_16x16x32_bf16 v[114:117], v[190:193], v[222:225], v[114:117]
	v_mfma_f32_16x16x32_bf16 v[110:113], v[168:171], v[230:233], v[110:113]
	v_mfma_f32_16x16x32_bf16 v[106:109], v[190:193], v[230:233], v[106:109]
	v_mfma_f32_16x16x32_bf16 v[102:105], v[168:171], v[246:249], v[102:105]
	v_mfma_f32_16x16x32_bf16 v[98:101], v[190:193], v[246:249], v[98:101]
	s_setprio 0
	s_setprio 1
	v_mfma_f32_16x16x32_bf16 v[76:79], v[194:197], v[210:213], v[76:79]
	v_mfma_f32_16x16x32_bf16 v[64:67], v[202:205], v[210:213], v[64:67]
	v_mfma_f32_16x16x32_bf16 v[60:63], v[194:197], v[218:221], v[60:63]
	v_mfma_f32_16x16x32_bf16 v[52:55], v[202:205], v[218:221], v[52:55]
	v_mfma_f32_16x16x32_bf16 v[44:47], v[194:197], v[226:229], v[44:47]
	v_mfma_f32_16x16x32_bf16 v[40:43], v[202:205], v[226:229], v[40:43]
	v_mfma_f32_16x16x32_bf16 v[36:39], v[194:197], v[242:245], v[36:39]
	v_mfma_f32_16x16x32_bf16 v[32:35], v[202:205], v[242:245], v[32:35]
	v_mfma_f32_16x16x32_bf16 v[76:79], v[198:201], v[214:217], v[76:79]
	v_mfma_f32_16x16x32_bf16 v[64:67], v[206:209], v[214:217], v[64:67]
	v_mfma_f32_16x16x32_bf16 v[60:63], v[198:201], v[222:225], v[60:63]
	v_mfma_f32_16x16x32_bf16 v[52:55], v[206:209], v[222:225], v[52:55]
	v_mfma_f32_16x16x32_bf16 v[44:47], v[198:201], v[230:233], v[44:47]
	v_mfma_f32_16x16x32_bf16 v[40:43], v[206:209], v[230:233], v[40:43]
	v_mfma_f32_16x16x32_bf16 v[36:39], v[198:201], v[246:249], v[36:39]
	v_mfma_f32_16x16x32_bf16 v[32:35], v[206:209], v[246:249], v[32:35]
	s_setprio 0
	s_barrier
	s_setprio 2
	s_add_i32 s62, s62, s40
	v_lshl_add_u64 v[154:155], s[34:35], 0, v[134:135]
	s_mov_b32 m0, s62
	ds_read_b128 v[210:213], v162 offset:16384
	ds_read_b128 v[214:217], v162 offset:17408
	ds_read_b128 v[218:221], v162 offset:18432
	ds_read_b128 v[222:225], v162 offset:19456
	ds_read_b128 v[226:229], v162 offset:20480
	ds_read_b128 v[230:233], v162 offset:21504
	ds_read_b128 v[242:245], v162 offset:22528
	ds_read_b128 v[246:249], v162 offset:23552
	global_load_lds_dwordx4 v[154:155], off
	s_add_i32 m0, s62, 0x2000
	s_add_u32 s62, s34, 0x40000
	v_lshl_add_u64 v[156:157], s[34:35], 0, v[130:131]
	s_addc_u32 s63, s35, 0
	s_add_i32 s64, s64, s40
	global_load_lds_dwordx4 v[156:157], off
	v_lshl_add_u64 v[158:159], s[62:63], 0, v[134:135]
	s_mov_b32 m0, s64
	v_lshl_add_u64 v[172:173], s[36:37], 0, v[132:133]
	global_load_lds_dwordx4 v[158:159], off
	v_lshl_add_u64 v[158:159], s[62:63], 0, v[130:131]
	s_add_i32 m0, s64, 0x2000
	s_nop 0
	global_load_lds_dwordx4 v[158:159], off
	v_lshl_add_u64 v[158:159], s[36:37], 0, v[136:137]
	s_mov_b32 m0, s43
	s_nop 0
	global_load_lds_dwordx4 v[158:159], off
	s_mov_b32 m0, s44
	s_nop 0
	global_load_lds_dwordx4 v[172:173], off
	s_setprio 0
	s_waitcnt vmcnt(8)
	s_waitcnt lgkmcnt(0)
	s_barrier
	s_setprio 1
	v_mfma_f32_16x16x32_bf16 v[92:95], v[164:167], v[210:213], v[92:95]
	v_mfma_f32_16x16x32_bf16 v[88:91], v[186:189], v[210:213], v[88:91]
	v_mfma_f32_16x16x32_bf16 v[84:87], v[164:167], v[218:221], v[84:87]
	v_mfma_f32_16x16x32_bf16 v[80:83], v[186:189], v[218:221], v[80:83]
	v_mfma_f32_16x16x32_bf16 v[72:75], v[164:167], v[226:229], v[72:75]
	v_mfma_f32_16x16x32_bf16 v[68:71], v[186:189], v[226:229], v[68:71]
	v_mfma_f32_16x16x32_bf16 v[56:59], v[164:167], v[242:245], v[56:59]
	v_mfma_f32_16x16x32_bf16 v[48:51], v[186:189], v[242:245], v[48:51]
	v_mfma_f32_16x16x32_bf16 v[92:95], v[168:171], v[214:217], v[92:95]
	v_mfma_f32_16x16x32_bf16 v[88:91], v[190:193], v[214:217], v[88:91]
	v_mfma_f32_16x16x32_bf16 v[84:87], v[168:171], v[222:225], v[84:87]
	v_mfma_f32_16x16x32_bf16 v[80:83], v[190:193], v[222:225], v[80:83]
	v_mfma_f32_16x16x32_bf16 v[72:75], v[168:171], v[230:233], v[72:75]
	v_mfma_f32_16x16x32_bf16 v[68:71], v[190:193], v[230:233], v[68:71]
	v_mfma_f32_16x16x32_bf16 v[56:59], v[168:171], v[246:249], v[56:59]
	v_mfma_f32_16x16x32_bf16 v[48:51], v[190:193], v[246:249], v[48:51]
	s_setprio 0
	s_setprio 1
	v_mfma_f32_16x16x32_bf16 v[28:31], v[194:197], v[210:213], v[28:31]
	v_mfma_f32_16x16x32_bf16 v[24:27], v[202:205], v[210:213], v[24:27]
	v_mfma_f32_16x16x32_bf16 v[20:23], v[194:197], v[218:221], v[20:23]
	v_mfma_f32_16x16x32_bf16 v[16:19], v[202:205], v[218:221], v[16:19]
	v_mfma_f32_16x16x32_bf16 v[12:15], v[194:197], v[226:229], v[12:15]
	v_mfma_f32_16x16x32_bf16 v[8:11], v[202:205], v[226:229], v[8:11]
	v_mfma_f32_16x16x32_bf16 v[4:7], v[194:197], v[242:245], v[4:7]
	v_mfma_f32_16x16x32_bf16 v[0:3], v[202:205], v[242:245], v[0:3]
	v_mfma_f32_16x16x32_bf16 v[28:31], v[198:201], v[214:217], v[28:31]
	v_mfma_f32_16x16x32_bf16 v[24:27], v[206:209], v[214:217], v[24:27]
	v_mfma_f32_16x16x32_bf16 v[20:23], v[198:201], v[222:225], v[20:23]
	v_mfma_f32_16x16x32_bf16 v[16:19], v[206:209], v[222:225], v[16:19]
	v_mfma_f32_16x16x32_bf16 v[12:15], v[198:201], v[230:233], v[12:15]
	v_mfma_f32_16x16x32_bf16 v[8:11], v[206:209], v[230:233], v[8:11]
	v_mfma_f32_16x16x32_bf16 v[4:7], v[198:201], v[246:249], v[4:7]
	v_mfma_f32_16x16x32_bf16 v[0:3], v[206:209], v[246:249], v[0:3]
	s_setprio 0
	s_barrier
	s_setprio 2
	s_add_i32 s62, 0, 0x18000
	v_add_u32_e32 v96, s62, v151
	s_add_i32 s63, 0, 0x1c000
	ds_read_b128 v[164:167], v96
	ds_read_b128 v[168:171], v96 offset:1024
	ds_read_b128 v[186:189], v96 offset:2048
	ds_read_b128 v[190:193], v96 offset:3072
	v_add_u32_e32 v96, s63, v151
	ds_read_b128 v[194:197], v96
	ds_read_b128 v[198:201], v96 offset:1024
	ds_read_b128 v[202:205], v96 offset:2048
	ds_read_b128 v[206:209], v96 offset:3072
	s_add_u32 s36, s36, 0x40000
	s_addc_u32 s37, s37, 0
	s_mov_b32 m0, s45
	v_lshl_add_u64 v[182:183], s[36:37], 0, v[136:137]
	ds_read_b128 v[210:213], v162 offset:32768
	ds_read_b128 v[214:217], v162 offset:33792
	ds_read_b128 v[218:221], v162 offset:34816
	ds_read_b128 v[222:225], v162 offset:35840
	ds_read_b128 v[226:229], v162 offset:36864
	ds_read_b128 v[230:233], v162 offset:37888
	ds_read_b128 v[242:245], v162 offset:38912
	ds_read_b128 v[246:249], v162 offset:39936
	global_load_lds_dwordx4 v[182:183], off
	v_lshl_add_u64 v[182:183], s[36:37], 0, v[132:133]
	s_mov_b32 m0, s46
	s_nop 0
	global_load_lds_dwordx4 v[182:183], off
	s_setprio 0
	s_waitcnt vmcnt(8)
	s_waitcnt lgkmcnt(0)
	s_barrier
	s_setprio 1
	v_mfma_f32_16x16x32_bf16 v[126:129], v[164:167], v[210:213], v[126:129]
	v_mfma_f32_16x16x32_bf16 v[122:125], v[186:189], v[210:213], v[122:125]
	v_mfma_f32_16x16x32_bf16 v[118:121], v[164:167], v[218:221], v[118:121]
	v_mfma_f32_16x16x32_bf16 v[114:117], v[186:189], v[218:221], v[114:117]
	v_mfma_f32_16x16x32_bf16 v[110:113], v[164:167], v[226:229], v[110:113]
	v_mfma_f32_16x16x32_bf16 v[106:109], v[186:189], v[226:229], v[106:109]
	v_mfma_f32_16x16x32_bf16 v[102:105], v[164:167], v[242:245], v[102:105]
	v_mfma_f32_16x16x32_bf16 v[98:101], v[186:189], v[242:245], v[98:101]
	v_mfma_f32_16x16x32_bf16 v[126:129], v[168:171], v[214:217], v[126:129]
	v_mfma_f32_16x16x32_bf16 v[122:125], v[190:193], v[214:217], v[122:125]
	v_mfma_f32_16x16x32_bf16 v[118:121], v[168:171], v[222:225], v[118:121]
	v_mfma_f32_16x16x32_bf16 v[114:117], v[190:193], v[222:225], v[114:117]
	v_mfma_f32_16x16x32_bf16 v[110:113], v[168:171], v[230:233], v[110:113]
	v_mfma_f32_16x16x32_bf16 v[106:109], v[190:193], v[230:233], v[106:109]
	v_mfma_f32_16x16x32_bf16 v[102:105], v[168:171], v[246:249], v[102:105]
	v_mfma_f32_16x16x32_bf16 v[98:101], v[190:193], v[246:249], v[98:101]
	s_setprio 0
	s_setprio 1
	v_mfma_f32_16x16x32_bf16 v[76:79], v[194:197], v[210:213], v[76:79]
	v_mfma_f32_16x16x32_bf16 v[64:67], v[202:205], v[210:213], v[64:67]
	v_mfma_f32_16x16x32_bf16 v[60:63], v[194:197], v[218:221], v[60:63]
	v_mfma_f32_16x16x32_bf16 v[52:55], v[202:205], v[218:221], v[52:55]
	v_mfma_f32_16x16x32_bf16 v[44:47], v[194:197], v[226:229], v[44:47]
	v_mfma_f32_16x16x32_bf16 v[40:43], v[202:205], v[226:229], v[40:43]
	v_mfma_f32_16x16x32_bf16 v[36:39], v[194:197], v[242:245], v[36:39]
	v_mfma_f32_16x16x32_bf16 v[32:35], v[202:205], v[242:245], v[32:35]
	v_mfma_f32_16x16x32_bf16 v[76:79], v[198:201], v[214:217], v[76:79]
	v_mfma_f32_16x16x32_bf16 v[64:67], v[206:209], v[214:217], v[64:67]
	v_mfma_f32_16x16x32_bf16 v[60:63], v[198:201], v[222:225], v[60:63]
	v_mfma_f32_16x16x32_bf16 v[52:55], v[206:209], v[222:225], v[52:55]
	v_mfma_f32_16x16x32_bf16 v[44:47], v[198:201], v[230:233], v[44:47]
	v_mfma_f32_16x16x32_bf16 v[40:43], v[206:209], v[230:233], v[40:43]
	v_mfma_f32_16x16x32_bf16 v[36:39], v[198:201], v[246:249], v[36:39]
	v_mfma_f32_16x16x32_bf16 v[32:35], v[206:209], v[246:249], v[32:35]
	s_setprio 0
	s_barrier
	s_setprio 2
	s_add_i32 s36, s62, s40
	v_lshl_add_u64 v[154:155], v[154:155], 0, s[16:17]
	s_mov_b32 m0, s36
	ds_read_b128 v[210:213], v162 offset:49152
	ds_read_b128 v[214:217], v162 offset:50176
	ds_read_b128 v[218:221], v162 offset:51200
	ds_read_b128 v[222:225], v162 offset:52224
	ds_read_b128 v[226:229], v162 offset:53248
	ds_read_b128 v[230:233], v162 offset:54272
	ds_read_b128 v[242:245], v162 offset:55296
	ds_read_b128 v[246:249], v162 offset:56320
	global_load_lds_dwordx4 v[154:155], off
	s_add_i32 m0, s36, 0x2000
	s_add_u32 s34, s34, 0x40080
	v_lshl_add_u64 v[154:155], v[156:157], 0, s[16:17]
	s_addc_u32 s35, s35, 0
	s_add_i32 s36, s63, s40
	global_load_lds_dwordx4 v[154:155], off
	v_lshl_add_u64 v[154:155], s[34:35], 0, v[134:135]
	s_mov_b32 m0, s36
	s_nop 0
	global_load_lds_dwordx4 v[154:155], off
	v_lshl_add_u64 v[154:155], s[34:35], 0, v[130:131]
	s_add_i32 m0, s36, 0x2000
	s_nop 0
	global_load_lds_dwordx4 v[154:155], off
	v_lshl_add_u64 v[154:155], v[158:159], 0, s[16:17]
	s_mov_b32 m0, s50
	s_nop 0
	global_load_lds_dwordx4 v[154:155], off
	v_lshl_add_u64 v[154:155], v[172:173], 0, s[16:17]
	s_mov_b32 m0, s51
	s_nop 0
	global_load_lds_dwordx4 v[154:155], off
	s_setprio 0
	s_waitcnt vmcnt(8)
	s_waitcnt lgkmcnt(0)
	s_barrier
	s_setprio 1
	v_mfma_f32_16x16x32_bf16 v[92:95], v[164:167], v[210:213], v[92:95]
	v_mfma_f32_16x16x32_bf16 v[88:91], v[186:189], v[210:213], v[88:91]
	v_mfma_f32_16x16x32_bf16 v[84:87], v[164:167], v[218:221], v[84:87]
	v_mfma_f32_16x16x32_bf16 v[80:83], v[186:189], v[218:221], v[80:83]
	v_mfma_f32_16x16x32_bf16 v[72:75], v[164:167], v[226:229], v[72:75]
	v_mfma_f32_16x16x32_bf16 v[68:71], v[186:189], v[226:229], v[68:71]
	v_mfma_f32_16x16x32_bf16 v[56:59], v[164:167], v[242:245], v[56:59]
	v_mfma_f32_16x16x32_bf16 v[48:51], v[186:189], v[242:245], v[48:51]
	v_mfma_f32_16x16x32_bf16 v[92:95], v[168:171], v[214:217], v[92:95]
	v_mfma_f32_16x16x32_bf16 v[88:91], v[190:193], v[214:217], v[88:91]
	v_mfma_f32_16x16x32_bf16 v[84:87], v[168:171], v[222:225], v[84:87]
	v_mfma_f32_16x16x32_bf16 v[80:83], v[190:193], v[222:225], v[80:83]
	v_mfma_f32_16x16x32_bf16 v[72:75], v[168:171], v[230:233], v[72:75]
	v_mfma_f32_16x16x32_bf16 v[68:71], v[190:193], v[230:233], v[68:71]
	v_mfma_f32_16x16x32_bf16 v[56:59], v[168:171], v[246:249], v[56:59]
	v_mfma_f32_16x16x32_bf16 v[48:51], v[190:193], v[246:249], v[48:51]
	s_setprio 0
	s_setprio 1
	v_mfma_f32_16x16x32_bf16 v[28:31], v[194:197], v[210:213], v[28:31]
	v_mfma_f32_16x16x32_bf16 v[24:27], v[202:205], v[210:213], v[24:27]
	v_mfma_f32_16x16x32_bf16 v[20:23], v[194:197], v[218:221], v[20:23]
	v_mfma_f32_16x16x32_bf16 v[16:19], v[202:205], v[218:221], v[16:19]
	v_mfma_f32_16x16x32_bf16 v[12:15], v[194:197], v[226:229], v[12:15]
	v_mfma_f32_16x16x32_bf16 v[8:11], v[202:205], v[226:229], v[8:11]
	v_mfma_f32_16x16x32_bf16 v[4:7], v[194:197], v[242:245], v[4:7]
	v_mfma_f32_16x16x32_bf16 v[0:3], v[202:205], v[242:245], v[0:3]
	v_mfma_f32_16x16x32_bf16 v[28:31], v[198:201], v[214:217], v[28:31]
	v_mfma_f32_16x16x32_bf16 v[24:27], v[206:209], v[214:217], v[24:27]
	v_mfma_f32_16x16x32_bf16 v[20:23], v[198:201], v[222:225], v[20:23]
	v_mfma_f32_16x16x32_bf16 v[16:19], v[206:209], v[222:225], v[16:19]
	v_mfma_f32_16x16x32_bf16 v[12:15], v[198:201], v[230:233], v[12:15]
	v_mfma_f32_16x16x32_bf16 v[8:11], v[206:209], v[230:233], v[8:11]
	v_mfma_f32_16x16x32_bf16 v[4:7], v[198:201], v[246:249], v[4:7]
	v_mfma_f32_16x16x32_bf16 v[0:3], v[206:209], v[246:249], v[0:3]
	s_add_i32 s61, s61, 2
	s_add_u32 s30, s30, 0x100
	s_addc_u32 s31, s31, 0
	s_add_u32 s59, s59, 0x100
	s_addc_u32 s60, s60, 0
	s_setprio 0
	s_barrier
	s_setprio 2
	s_cmp_gt_u32 s61, 13
	s_cbranch_scc0 .LBB0_361
	s_and_b64 vcc, exec, s[20:21]
	s_cbranch_vccz .LBB0_364
	s_barrier

.LBB0_393:
	s_add_i32 s57, 0, 0x10000
	v_add_u32_e32 v151, s57, v141
	s_add_i32 s60, 0, 0x14000
	ds_read_b128 v[162:165], v151
	ds_read_b128 v[166:169], v151 offset:1024
	ds_read_b128 v[170:173], v151 offset:2048
	ds_read_b128 v[186:189], v151 offset:3072
	v_add_u32_e32 v151, s60, v141
	ds_read_b128 v[190:193], v151
	ds_read_b128 v[194:197], v151 offset:1024
	ds_read_b128 v[198:201], v151 offset:2048
	ds_read_b128 v[202:205], v151 offset:3072
	s_add_u32 s26, s14, 0xfffc0080
	s_addc_u32 s27, s15, -1
	s_cmp_eq_u32 s56, 12
	s_cselect_b32 s29, s19, s27
	s_cselect_b32 s28, s52, s26
	s_cselect_b32 s27, s5, s55
	s_cselect_b32 s26, s53, s54
	v_lshl_add_u64 v[152:153], s[14:15], 0, v[146:147]
	s_add_i32 m0, s39, 0xc000
	ds_read_b128 v[206:209], v150
	ds_read_b128 v[210:213], v150 offset:1024
	ds_read_b128 v[214:217], v150 offset:2048
	ds_read_b128 v[218:221], v150 offset:3072
	ds_read_b128 v[222:225], v150 offset:4096
	ds_read_b128 v[226:229], v150 offset:5120
	ds_read_b128 v[230:233], v150 offset:6144
	ds_read_b128 v[242:245], v150 offset:7168
	global_load_lds_dwordx4 v[152:153], off
	v_lshl_add_u64 v[152:153], s[14:15], 0, v[148:149]
	s_add_i32 m0, s39, 0xe000
	s_nop 0
	global_load_lds_dwordx4 v[152:153], off
	s_setprio 0
	s_waitcnt vmcnt(8)
	s_waitcnt lgkmcnt(0)
	s_barrier
	s_setprio 1
	v_mfma_f32_16x16x32_bf16 v[126:129], v[162:165], v[206:209], v[126:129]
	v_mfma_f32_16x16x32_bf16 v[122:125], v[170:173], v[206:209], v[122:125]
	v_mfma_f32_16x16x32_bf16 v[118:121], v[162:165], v[214:217], v[118:121]
	v_mfma_f32_16x16x32_bf16 v[114:117], v[170:173], v[214:217], v[114:117]
	v_mfma_f32_16x16x32_bf16 v[110:113], v[162:165], v[222:225], v[110:113]
	v_mfma_f32_16x16x32_bf16 v[106:109], v[170:173], v[222:225], v[106:109]
	v_mfma_f32_16x16x32_bf16 v[102:105], v[162:165], v[230:233], v[102:105]
	v_mfma_f32_16x16x32_bf16 v[98:101], v[170:173], v[230:233], v[98:101]
	v_mfma_f32_16x16x32_bf16 v[126:129], v[166:169], v[210:213], v[126:129]
	v_mfma_f32_16x16x32_bf16 v[122:125], v[186:189], v[210:213], v[122:125]
	v_mfma_f32_16x16x32_bf16 v[118:121], v[166:169], v[218:221], v[118:121]
	v_mfma_f32_16x16x32_bf16 v[114:117], v[186:189], v[218:221], v[114:117]
	v_mfma_f32_16x16x32_bf16 v[110:113], v[166:169], v[226:229], v[110:113]
	v_mfma_f32_16x16x32_bf16 v[106:109], v[186:189], v[226:229], v[106:109]
	v_mfma_f32_16x16x32_bf16 v[102:105], v[166:169], v[242:245], v[102:105]
	v_mfma_f32_16x16x32_bf16 v[98:101], v[186:189], v[242:245], v[98:101]
	s_setprio 0
	s_setprio 1
	v_mfma_f32_16x16x32_bf16 v[68:71], v[190:193], v[206:209], v[68:71]
	v_mfma_f32_16x16x32_bf16 v[64:67], v[198:201], v[206:209], v[64:67]
	v_mfma_f32_16x16x32_bf16 v[52:55], v[190:193], v[214:217], v[52:55]
	v_mfma_f32_16x16x32_bf16 v[48:51], v[198:201], v[214:217], v[48:51]
	v_mfma_f32_16x16x32_bf16 v[44:47], v[190:193], v[222:225], v[44:47]
	v_mfma_f32_16x16x32_bf16 v[40:43], v[198:201], v[222:225], v[40:43]
	v_mfma_f32_16x16x32_bf16 v[36:39], v[190:193], v[230:233], v[36:39]
	v_mfma_f32_16x16x32_bf16 v[32:35], v[198:201], v[230:233], v[32:35]
	v_mfma_f32_16x16x32_bf16 v[68:71], v[194:197], v[210:213], v[68:71]
	v_mfma_f32_16x16x32_bf16 v[64:67], v[202:205], v[210:213], v[64:67]
	v_mfma_f32_16x16x32_bf16 v[52:55], v[194:197], v[218:221], v[52:55]
	v_mfma_f32_16x16x32_bf16 v[48:51], v[202:205], v[218:221], v[48:51]
	v_mfma_f32_16x16x32_bf16 v[44:47], v[194:197], v[226:229], v[44:47]
	v_mfma_f32_16x16x32_bf16 v[40:43], v[202:205], v[226:229], v[40:43]
	v_mfma_f32_16x16x32_bf16 v[36:39], v[194:197], v[242:245], v[36:39]
	v_mfma_f32_16x16x32_bf16 v[32:35], v[202:205], v[242:245], v[32:35]
	s_setprio 0
	s_barrier
	s_setprio 2
	s_add_i32 s57, s57, s36
	v_lshl_add_u64 v[152:153], s[26:27], 0, v[96:97]
	s_mov_b32 m0, s57
	ds_read_b128 v[206:209], v150 offset:16384
	ds_read_b128 v[210:213], v150 offset:17408
	ds_read_b128 v[214:217], v150 offset:18432
	ds_read_b128 v[218:221], v150 offset:19456
	ds_read_b128 v[222:225], v150 offset:20480
	ds_read_b128 v[226:229], v150 offset:21504
	ds_read_b128 v[230:233], v150 offset:22528
	ds_read_b128 v[242:245], v150 offset:23552
	global_load_lds_dwordx4 v[152:153], off
	s_add_i32 m0, s57, 0x2000
	s_add_u32 s58, s26, 0x40000
	v_lshl_add_u64 v[154:155], s[26:27], 0, v[130:131]
	s_addc_u32 s59, s27, 0
	s_add_i32 s57, s60, s36
	global_load_lds_dwordx4 v[154:155], off
	v_lshl_add_u64 v[156:157], s[58:59], 0, v[96:97]
	s_mov_b32 m0, s57
	v_lshl_add_u64 v[158:159], s[28:29], 0, v[132:133]
	global_load_lds_dwordx4 v[156:157], off
	v_lshl_add_u64 v[156:157], s[58:59], 0, v[130:131]
	s_add_i32 m0, s57, 0x2000
	s_nop 0
	global_load_lds_dwordx4 v[156:157], off
	v_lshl_add_u64 v[156:157], s[28:29], 0, v[134:135]
	s_mov_b32 m0, s39
	s_nop 0
	global_load_lds_dwordx4 v[156:157], off
	s_mov_b32 m0, s40
	s_nop 0
	global_load_lds_dwordx4 v[158:159], off
	s_setprio 0
	s_waitcnt vmcnt(8)
	s_waitcnt lgkmcnt(0)
	s_barrier
	s_setprio 1
	v_mfma_f32_16x16x32_bf16 v[92:95], v[162:165], v[206:209], v[92:95]
	v_mfma_f32_16x16x32_bf16 v[88:91], v[170:173], v[206:209], v[88:91]
	v_mfma_f32_16x16x32_bf16 v[84:87], v[162:165], v[214:217], v[84:87]
	v_mfma_f32_16x16x32_bf16 v[80:83], v[170:173], v[214:217], v[80:83]
	v_mfma_f32_16x16x32_bf16 v[76:79], v[162:165], v[222:225], v[76:79]
	v_mfma_f32_16x16x32_bf16 v[72:75], v[170:173], v[222:225], v[72:75]
	v_mfma_f32_16x16x32_bf16 v[60:63], v[162:165], v[230:233], v[60:63]
	v_mfma_f32_16x16x32_bf16 v[56:59], v[170:173], v[230:233], v[56:59]
	v_mfma_f32_16x16x32_bf16 v[92:95], v[166:169], v[210:213], v[92:95]
	v_mfma_f32_16x16x32_bf16 v[88:91], v[186:189], v[210:213], v[88:91]
	v_mfma_f32_16x16x32_bf16 v[84:87], v[166:169], v[218:221], v[84:87]
	v_mfma_f32_16x16x32_bf16 v[80:83], v[186:189], v[218:221], v[80:83]
	v_mfma_f32_16x16x32_bf16 v[76:79], v[166:169], v[226:229], v[76:79]
	v_mfma_f32_16x16x32_bf16 v[72:75], v[186:189], v[226:229], v[72:75]
	v_mfma_f32_16x16x32_bf16 v[60:63], v[166:169], v[242:245], v[60:63]
	v_mfma_f32_16x16x32_bf16 v[56:59], v[186:189], v[242:245], v[56:59]
	s_setprio 0
	s_setprio 1
	v_mfma_f32_16x16x32_bf16 v[28:31], v[190:193], v[206:209], v[28:31]
	v_mfma_f32_16x16x32_bf16 v[24:27], v[198:201], v[206:209], v[24:27]
	v_mfma_f32_16x16x32_bf16 v[20:23], v[190:193], v[214:217], v[20:23]
	v_mfma_f32_16x16x32_bf16 v[16:19], v[198:201], v[214:217], v[16:19]
	v_mfma_f32_16x16x32_bf16 v[12:15], v[190:193], v[222:225], v[12:15]
	v_mfma_f32_16x16x32_bf16 v[8:11], v[198:201], v[222:225], v[8:11]
	v_mfma_f32_16x16x32_bf16 v[4:7], v[190:193], v[230:233], v[4:7]
	v_mfma_f32_16x16x32_bf16 v[0:3], v[198:201], v[230:233], v[0:3]
	v_mfma_f32_16x16x32_bf16 v[28:31], v[194:197], v[210:213], v[28:31]
	v_mfma_f32_16x16x32_bf16 v[24:27], v[202:205], v[210:213], v[24:27]
	v_mfma_f32_16x16x32_bf16 v[20:23], v[194:197], v[218:221], v[20:23]
	v_mfma_f32_16x16x32_bf16 v[16:19], v[202:205], v[218:221], v[16:19]
	v_mfma_f32_16x16x32_bf16 v[12:15], v[194:197], v[226:229], v[12:15]
	v_mfma_f32_16x16x32_bf16 v[8:11], v[202:205], v[226:229], v[8:11]
	v_mfma_f32_16x16x32_bf16 v[4:7], v[194:197], v[242:245], v[4:7]
	v_mfma_f32_16x16x32_bf16 v[0:3], v[202:205], v[242:245], v[0:3]
	s_setprio 0
	s_barrier
	s_setprio 2
	s_add_i32 s57, 0, 0x18000
	v_add_u32_e32 v151, s57, v141
	s_add_i32 s58, 0, 0x1c000
	ds_read_b128 v[162:165], v151
	ds_read_b128 v[166:169], v151 offset:1024
	ds_read_b128 v[170:173], v151 offset:2048
	ds_read_b128 v[186:189], v151 offset:3072
	v_add_u32_e32 v151, s58, v141
	ds_read_b128 v[190:193], v151
	ds_read_b128 v[194:197], v151 offset:1024
	ds_read_b128 v[198:201], v151 offset:2048
	ds_read_b128 v[202:205], v151 offset:3072
	s_add_u32 s28, s28, 0x40000
	s_addc_u32 s29, s29, 0
	s_mov_b32 m0, s41
	v_lshl_add_u64 v[182:183], s[28:29], 0, v[134:135]
	ds_read_b128 v[206:209], v150 offset:32768
	ds_read_b128 v[210:213], v150 offset:33792
	ds_read_b128 v[214:217], v150 offset:34816
	ds_read_b128 v[218:221], v150 offset:35840
	ds_read_b128 v[222:225], v150 offset:36864
	ds_read_b128 v[226:229], v150 offset:37888
	ds_read_b128 v[230:233], v150 offset:38912
	ds_read_b128 v[242:245], v150 offset:39936
	global_load_lds_dwordx4 v[182:183], off
	v_lshl_add_u64 v[182:183], s[28:29], 0, v[132:133]
	s_mov_b32 m0, s42
	s_nop 0
	global_load_lds_dwordx4 v[182:183], off
	s_setprio 0
	s_waitcnt vmcnt(8)
	s_waitcnt lgkmcnt(0)
	s_barrier
	s_setprio 1
	v_mfma_f32_16x16x32_bf16 v[126:129], v[162:165], v[206:209], v[126:129]
	v_mfma_f32_16x16x32_bf16 v[122:125], v[170:173], v[206:209], v[122:125]
	v_mfma_f32_16x16x32_bf16 v[118:121], v[162:165], v[214:217], v[118:121]
	v_mfma_f32_16x16x32_bf16 v[114:117], v[170:173], v[214:217], v[114:117]
	v_mfma_f32_16x16x32_bf16 v[110:113], v[162:165], v[222:225], v[110:113]
	v_mfma_f32_16x16x32_bf16 v[106:109], v[170:173], v[222:225], v[106:109]
	v_mfma_f32_16x16x32_bf16 v[102:105], v[162:165], v[230:233], v[102:105]
	v_mfma_f32_16x16x32_bf16 v[98:101], v[170:173], v[230:233], v[98:101]
	v_mfma_f32_16x16x32_bf16 v[126:129], v[166:169], v[210:213], v[126:129]
	v_mfma_f32_16x16x32_bf16 v[122:125], v[186:189], v[210:213], v[122:125]
	v_mfma_f32_16x16x32_bf16 v[118:121], v[166:169], v[218:221], v[118:121]
	v_mfma_f32_16x16x32_bf16 v[114:117], v[186:189], v[218:221], v[114:117]
	v_mfma_f32_16x16x32_bf16 v[110:113], v[166:169], v[226:229], v[110:113]
	v_mfma_f32_16x16x32_bf16 v[106:109], v[186:189], v[226:229], v[106:109]
	v_mfma_f32_16x16x32_bf16 v[102:105], v[166:169], v[242:245], v[102:105]
	v_mfma_f32_16x16x32_bf16 v[98:101], v[186:189], v[242:245], v[98:101]
	s_setprio 0
	s_setprio 1
	v_mfma_f32_16x16x32_bf16 v[68:71], v[190:193], v[206:209], v[68:71]
	v_mfma_f32_16x16x32_bf16 v[64:67], v[198:201], v[206:209], v[64:67]
	v_mfma_f32_16x16x32_bf16 v[52:55], v[190:193], v[214:217], v[52:55]
	v_mfma_f32_16x16x32_bf16 v[48:51], v[198:201], v[214:217], v[48:51]
	v_mfma_f32_16x16x32_bf16 v[44:47], v[190:193], v[222:225], v[44:47]
	v_mfma_f32_16x16x32_bf16 v[40:43], v[198:201], v[222:225], v[40:43]
	v_mfma_f32_16x16x32_bf16 v[36:39], v[190:193], v[230:233], v[36:39]
	v_mfma_f32_16x16x32_bf16 v[32:35], v[198:201], v[230:233], v[32:35]
	v_mfma_f32_16x16x32_bf16 v[68:71], v[194:197], v[210:213], v[68:71]
	v_mfma_f32_16x16x32_bf16 v[64:67], v[202:205], v[210:213], v[64:67]
	v_mfma_f32_16x16x32_bf16 v[52:55], v[194:197], v[218:221], v[52:55]
	v_mfma_f32_16x16x32_bf16 v[48:51], v[202:205], v[218:221], v[48:51]
	v_mfma_f32_16x16x32_bf16 v[44:47], v[194:197], v[226:229], v[44:47]
	v_mfma_f32_16x16x32_bf16 v[40:43], v[202:205], v[226:229], v[40:43]
	v_mfma_f32_16x16x32_bf16 v[36:39], v[194:197], v[242:245], v[36:39]
	v_mfma_f32_16x16x32_bf16 v[32:35], v[202:205], v[242:245], v[32:35]
	s_setprio 0
	s_barrier
	s_setprio 2
	s_add_i32 s28, s57, s36
	v_lshl_add_u64 v[152:153], v[152:153], 0, s[16:17]
	s_mov_b32 m0, s28
	ds_read_b128 v[206:209], v150 offset:49152
	ds_read_b128 v[210:213], v150 offset:50176
	ds_read_b128 v[214:217], v150 offset:51200
	ds_read_b128 v[218:221], v150 offset:52224
	ds_read_b128 v[222:225], v150 offset:53248
	ds_read_b128 v[226:229], v150 offset:54272
	ds_read_b128 v[230:233], v150 offset:55296
	ds_read_b128 v[242:245], v150 offset:56320
	global_load_lds_dwordx4 v[152:153], off
	s_add_i32 m0, s28, 0x2000
	s_add_u32 s26, s26, 0x40080
	v_lshl_add_u64 v[152:153], v[154:155], 0, s[16:17]
	s_addc_u32 s27, s27, 0
	s_add_i32 s28, s58, s36
	global_load_lds_dwordx4 v[152:153], off
	v_lshl_add_u64 v[152:153], s[26:27], 0, v[96:97]
	s_mov_b32 m0, s28
	s_nop 0
	global_load_lds_dwordx4 v[152:153], off
	v_lshl_add_u64 v[152:153], s[26:27], 0, v[130:131]
	s_add_i32 m0, s28, 0x2000
	s_nop 0
	global_load_lds_dwordx4 v[152:153], off
	v_lshl_add_u64 v[152:153], v[156:157], 0, s[16:17]
	s_mov_b32 m0, s45
	s_nop 0
	global_load_lds_dwordx4 v[152:153], off
	v_lshl_add_u64 v[152:153], v[158:159], 0, s[16:17]
	s_mov_b32 m0, s46
	s_nop 0
	global_load_lds_dwordx4 v[152:153], off
	s_setprio 0
	s_waitcnt vmcnt(8)
	s_waitcnt lgkmcnt(0)
	s_barrier
	s_setprio 1
	v_mfma_f32_16x16x32_bf16 v[92:95], v[162:165], v[206:209], v[92:95]
	v_mfma_f32_16x16x32_bf16 v[88:91], v[170:173], v[206:209], v[88:91]
	v_mfma_f32_16x16x32_bf16 v[84:87], v[162:165], v[214:217], v[84:87]
	v_mfma_f32_16x16x32_bf16 v[80:83], v[170:173], v[214:217], v[80:83]
	v_mfma_f32_16x16x32_bf16 v[76:79], v[162:165], v[222:225], v[76:79]
	v_mfma_f32_16x16x32_bf16 v[72:75], v[170:173], v[222:225], v[72:75]
	v_mfma_f32_16x16x32_bf16 v[60:63], v[162:165], v[230:233], v[60:63]
	v_mfma_f32_16x16x32_bf16 v[56:59], v[170:173], v[230:233], v[56:59]
	v_mfma_f32_16x16x32_bf16 v[92:95], v[166:169], v[210:213], v[92:95]
	v_mfma_f32_16x16x32_bf16 v[88:91], v[186:189], v[210:213], v[88:91]
	v_mfma_f32_16x16x32_bf16 v[84:87], v[166:169], v[218:221], v[84:87]
	v_mfma_f32_16x16x32_bf16 v[80:83], v[186:189], v[218:221], v[80:83]
	v_mfma_f32_16x16x32_bf16 v[76:79], v[166:169], v[226:229], v[76:79]
	v_mfma_f32_16x16x32_bf16 v[72:75], v[186:189], v[226:229], v[72:75]
	v_mfma_f32_16x16x32_bf16 v[60:63], v[166:169], v[242:245], v[60:63]
	v_mfma_f32_16x16x32_bf16 v[56:59], v[186:189], v[242:245], v[56:59]
	s_setprio 0
	s_setprio 1
	v_mfma_f32_16x16x32_bf16 v[28:31], v[190:193], v[206:209], v[28:31]
	v_mfma_f32_16x16x32_bf16 v[24:27], v[198:201], v[206:209], v[24:27]
	v_mfma_f32_16x16x32_bf16 v[20:23], v[190:193], v[214:217], v[20:23]
	v_mfma_f32_16x16x32_bf16 v[16:19], v[198:201], v[214:217], v[16:19]
	v_mfma_f32_16x16x32_bf16 v[12:15], v[190:193], v[222:225], v[12:15]
	v_mfma_f32_16x16x32_bf16 v[8:11], v[198:201], v[222:225], v[8:11]
	v_mfma_f32_16x16x32_bf16 v[4:7], v[190:193], v[230:233], v[4:7]
	v_mfma_f32_16x16x32_bf16 v[0:3], v[198:201], v[230:233], v[0:3]
	v_mfma_f32_16x16x32_bf16 v[28:31], v[194:197], v[210:213], v[28:31]
	v_mfma_f32_16x16x32_bf16 v[24:27], v[202:205], v[210:213], v[24:27]
	v_mfma_f32_16x16x32_bf16 v[20:23], v[194:197], v[218:221], v[20:23]
	v_mfma_f32_16x16x32_bf16 v[16:19], v[202:205], v[218:221], v[16:19]
	v_mfma_f32_16x16x32_bf16 v[12:15], v[194:197], v[226:229], v[12:15]
	v_mfma_f32_16x16x32_bf16 v[8:11], v[202:205], v[226:229], v[8:11]
	v_mfma_f32_16x16x32_bf16 v[4:7], v[194:197], v[242:245], v[4:7]
	v_mfma_f32_16x16x32_bf16 v[0:3], v[202:205], v[242:245], v[0:3]
	s_add_i32 s56, s56, 2
	s_add_u32 s14, s14, 0x100
	s_addc_u32 s15, s15, 0
	s_add_u32 s54, s54, 0x100
	s_addc_u32 s55, s55, 0
	s_setprio 0
	s_barrier
	s_setprio 2
	s_cmp_gt_u32 s56, 13
	s_cbranch_scc0 .LBB0_393
	s_and_b64 vcc, exec, s[12:13]
	s_cbranch_vccz .LBB0_396
	s_barrier

.LBB0_427:
	s_add_i32 s62, 0, 0x10000
	v_add_u32_e32 v154, s62, v169
	s_add_i32 s64, 0, 0x14000
	ds_read_b128 v[142:145], v154
	ds_read_b128 v[146:149], v154 offset:1024
	ds_read_b128 v[150:153], v154 offset:2048
	ds_read_b128 v[162:165], v154 offset:3072
	v_add_u32_e32 v154, s64, v169
	ds_read_b128 v[186:189], v154
	ds_read_b128 v[190:193], v154 offset:1024
	ds_read_b128 v[194:197], v154 offset:2048
	ds_read_b128 v[198:201], v154 offset:3072
	s_add_u32 s14, s4, 0xfffc0080
	s_addc_u32 s15, s5, -1
	s_cmp_eq_u32 s61, 12
	s_cselect_b32 s37, s29, s15
	s_cselect_b32 s36, s57, s14
	s_cselect_b32 s15, s27, s60
	s_cselect_b32 s14, s58, s59
	v_lshl_add_u64 v[154:155], s[4:5], 0, v[138:139]
	s_add_i32 m0, s43, 0xc000
	ds_read_b128 v[202:205], v173
	ds_read_b128 v[206:209], v173 offset:1024
	ds_read_b128 v[210:213], v173 offset:2048
	ds_read_b128 v[214:217], v173 offset:3072
	ds_read_b128 v[218:221], v173 offset:4096
	ds_read_b128 v[222:225], v173 offset:5120
	ds_read_b128 v[226:229], v173 offset:6144
	ds_read_b128 v[230:233], v173 offset:7168
	global_load_lds_dwordx4 v[154:155], off
	v_lshl_add_u64 v[154:155], s[4:5], 0, v[140:141]
	s_add_i32 m0, s43, 0xe000
	s_nop 0
	global_load_lds_dwordx4 v[154:155], off
	s_setprio 0
	s_waitcnt vmcnt(8)
	s_waitcnt lgkmcnt(0)
	s_barrier
	s_setprio 1
	v_mfma_f32_16x16x32_bf16 v[126:129], v[142:145], v[202:205], v[126:129]
	v_mfma_f32_16x16x32_bf16 v[122:125], v[150:153], v[202:205], v[122:125]
	v_mfma_f32_16x16x32_bf16 v[110:113], v[142:145], v[210:213], v[110:113]
	v_mfma_f32_16x16x32_bf16 v[106:109], v[150:153], v[210:213], v[106:109]
	v_mfma_f32_16x16x32_bf16 v[92:95], v[142:145], v[218:221], v[92:95]
	v_mfma_f32_16x16x32_bf16 v[88:91], v[150:153], v[218:221], v[88:91]
	v_mfma_f32_16x16x32_bf16 v[76:79], v[142:145], v[226:229], v[76:79]
	v_mfma_f32_16x16x32_bf16 v[72:75], v[150:153], v[226:229], v[72:75]
	v_mfma_f32_16x16x32_bf16 v[126:129], v[146:149], v[206:209], v[126:129]
	v_mfma_f32_16x16x32_bf16 v[122:125], v[162:165], v[206:209], v[122:125]
	v_mfma_f32_16x16x32_bf16 v[110:113], v[146:149], v[214:217], v[110:113]
	v_mfma_f32_16x16x32_bf16 v[106:109], v[162:165], v[214:217], v[106:109]
	v_mfma_f32_16x16x32_bf16 v[92:95], v[146:149], v[222:225], v[92:95]
	v_mfma_f32_16x16x32_bf16 v[88:91], v[162:165], v[222:225], v[88:91]
	v_mfma_f32_16x16x32_bf16 v[76:79], v[146:149], v[230:233], v[76:79]
	v_mfma_f32_16x16x32_bf16 v[72:75], v[162:165], v[230:233], v[72:75]
	s_setprio 0
	s_setprio 1
	v_mfma_f32_16x16x32_bf16 v[118:121], v[186:189], v[202:205], v[118:121]
	v_mfma_f32_16x16x32_bf16 v[114:117], v[194:197], v[202:205], v[114:117]
	v_mfma_f32_16x16x32_bf16 v[102:105], v[186:189], v[210:213], v[102:105]
	v_mfma_f32_16x16x32_bf16 v[98:101], v[194:197], v[210:213], v[98:101]
	v_mfma_f32_16x16x32_bf16 v[84:87], v[186:189], v[218:221], v[84:87]
	v_mfma_f32_16x16x32_bf16 v[80:83], v[194:197], v[218:221], v[80:83]
	v_mfma_f32_16x16x32_bf16 v[68:71], v[186:189], v[226:229], v[68:71]
	v_mfma_f32_16x16x32_bf16 v[64:67], v[194:197], v[226:229], v[64:67]
	v_mfma_f32_16x16x32_bf16 v[118:121], v[190:193], v[206:209], v[118:121]
	v_mfma_f32_16x16x32_bf16 v[114:117], v[198:201], v[206:209], v[114:117]
	v_mfma_f32_16x16x32_bf16 v[102:105], v[190:193], v[214:217], v[102:105]
	v_mfma_f32_16x16x32_bf16 v[98:101], v[198:201], v[214:217], v[98:101]
	v_mfma_f32_16x16x32_bf16 v[84:87], v[190:193], v[222:225], v[84:87]
	v_mfma_f32_16x16x32_bf16 v[80:83], v[198:201], v[222:225], v[80:83]
	v_mfma_f32_16x16x32_bf16 v[68:71], v[190:193], v[230:233], v[68:71]
	v_mfma_f32_16x16x32_bf16 v[64:67], v[198:201], v[230:233], v[64:67]
	s_setprio 0
	s_barrier
	s_setprio 2
	s_add_i32 s62, s62, s42
	v_lshl_add_u64 v[154:155], s[14:15], 0, v[96:97]
	s_mov_b32 m0, s62
	ds_read_b128 v[202:205], v173 offset:16384
	ds_read_b128 v[206:209], v173 offset:17408
	ds_read_b128 v[210:213], v173 offset:18432
	ds_read_b128 v[214:217], v173 offset:19456
	ds_read_b128 v[218:221], v173 offset:20480
	ds_read_b128 v[222:225], v173 offset:21504
	ds_read_b128 v[226:229], v173 offset:22528
	ds_read_b128 v[230:233], v173 offset:23552
	global_load_lds_dwordx4 v[154:155], off
	s_add_i32 m0, s62, 0x2000
	s_add_u32 s62, s14, 0x40000
	v_lshl_add_u64 v[156:157], s[14:15], 0, v[130:131]
	s_addc_u32 s63, s15, 0
	s_add_i32 s64, s64, s42
	global_load_lds_dwordx4 v[156:157], off
	v_lshl_add_u64 v[158:159], s[62:63], 0, v[96:97]
	s_mov_b32 m0, s64
	v_lshl_add_u64 v[166:167], s[36:37], 0, v[132:133]
	global_load_lds_dwordx4 v[158:159], off
	v_lshl_add_u64 v[158:159], s[62:63], 0, v[130:131]
	s_add_i32 m0, s64, 0x2000
	s_nop 0
	global_load_lds_dwordx4 v[158:159], off
	v_lshl_add_u64 v[158:159], s[36:37], 0, v[134:135]
	s_mov_b32 m0, s43
	s_nop 0
	global_load_lds_dwordx4 v[158:159], off
	s_mov_b32 m0, s44
	s_nop 0
	global_load_lds_dwordx4 v[166:167], off
	s_setprio 0
	s_waitcnt vmcnt(8)
	s_waitcnt lgkmcnt(0)
	s_barrier
	s_setprio 1
	v_mfma_f32_16x16x32_bf16 v[60:63], v[142:145], v[202:205], v[60:63]
	v_mfma_f32_16x16x32_bf16 v[56:59], v[150:153], v[202:205], v[56:59]
	v_mfma_f32_16x16x32_bf16 v[44:47], v[142:145], v[210:213], v[44:47]
	v_mfma_f32_16x16x32_bf16 v[40:43], v[150:153], v[210:213], v[40:43]
	v_mfma_f32_16x16x32_bf16 v[28:31], v[142:145], v[218:221], v[28:31]
	v_mfma_f32_16x16x32_bf16 v[24:27], v[150:153], v[218:221], v[24:27]
	v_mfma_f32_16x16x32_bf16 v[12:15], v[142:145], v[226:229], v[12:15]
	v_mfma_f32_16x16x32_bf16 v[8:11], v[150:153], v[226:229], v[8:11]
	v_mfma_f32_16x16x32_bf16 v[60:63], v[146:149], v[206:209], v[60:63]
	v_mfma_f32_16x16x32_bf16 v[56:59], v[162:165], v[206:209], v[56:59]
	v_mfma_f32_16x16x32_bf16 v[44:47], v[146:149], v[214:217], v[44:47]
	v_mfma_f32_16x16x32_bf16 v[40:43], v[162:165], v[214:217], v[40:43]
	v_mfma_f32_16x16x32_bf16 v[28:31], v[146:149], v[222:225], v[28:31]
	v_mfma_f32_16x16x32_bf16 v[24:27], v[162:165], v[222:225], v[24:27]
	v_mfma_f32_16x16x32_bf16 v[12:15], v[146:149], v[230:233], v[12:15]
	v_mfma_f32_16x16x32_bf16 v[8:11], v[162:165], v[230:233], v[8:11]
	s_setprio 0
	s_setprio 1
	v_mfma_f32_16x16x32_bf16 v[52:55], v[186:189], v[202:205], v[52:55]
	v_mfma_f32_16x16x32_bf16 v[48:51], v[194:197], v[202:205], v[48:51]
	v_mfma_f32_16x16x32_bf16 v[36:39], v[186:189], v[210:213], v[36:39]
	v_mfma_f32_16x16x32_bf16 v[32:35], v[194:197], v[210:213], v[32:35]
	v_mfma_f32_16x16x32_bf16 v[20:23], v[186:189], v[218:221], v[20:23]
	v_mfma_f32_16x16x32_bf16 v[16:19], v[194:197], v[218:221], v[16:19]
	v_mfma_f32_16x16x32_bf16 v[4:7], v[186:189], v[226:229], v[4:7]
	v_mfma_f32_16x16x32_bf16 v[0:3], v[194:197], v[226:229], v[0:3]
	v_mfma_f32_16x16x32_bf16 v[52:55], v[190:193], v[206:209], v[52:55]
	v_mfma_f32_16x16x32_bf16 v[48:51], v[198:201], v[206:209], v[48:51]
	v_mfma_f32_16x16x32_bf16 v[36:39], v[190:193], v[214:217], v[36:39]
	v_mfma_f32_16x16x32_bf16 v[32:35], v[198:201], v[214:217], v[32:35]
	v_mfma_f32_16x16x32_bf16 v[20:23], v[190:193], v[222:225], v[20:23]
	v_mfma_f32_16x16x32_bf16 v[16:19], v[198:201], v[222:225], v[16:19]
	v_mfma_f32_16x16x32_bf16 v[4:7], v[190:193], v[230:233], v[4:7]
	v_mfma_f32_16x16x32_bf16 v[0:3], v[198:201], v[230:233], v[0:3]
	s_setprio 0
	s_barrier
	s_setprio 2
	s_add_i32 s62, 0, 0x18000
	s_add_i32 s63, 0, 0x1c000
	v_add_u32_e32 v162, s62, v169
	v_add_u32_e32 v182, s63, v169
	ds_read_b128 v[142:145], v162
	ds_read_b128 v[146:149], v162 offset:1024
	ds_read_b128 v[150:153], v162 offset:2048
	ds_read_b128 v[162:165], v162 offset:3072
	ds_read_b128 v[186:189], v182
	ds_read_b128 v[190:193], v182 offset:1024
	ds_read_b128 v[194:197], v182 offset:2048
	ds_read_b128 v[198:201], v182 offset:3072
	s_add_u32 s36, s36, 0x40000
	s_addc_u32 s37, s37, 0
	s_mov_b32 m0, s45
	v_lshl_add_u64 v[182:183], s[36:37], 0, v[134:135]
	ds_read_b128 v[202:205], v173 offset:32768
	ds_read_b128 v[206:209], v173 offset:33792
	ds_read_b128 v[210:213], v173 offset:34816
	ds_read_b128 v[214:217], v173 offset:35840
	ds_read_b128 v[218:221], v173 offset:36864
	ds_read_b128 v[222:225], v173 offset:37888
	ds_read_b128 v[226:229], v173 offset:38912
	ds_read_b128 v[230:233], v173 offset:39936
	global_load_lds_dwordx4 v[182:183], off
	v_lshl_add_u64 v[182:183], s[36:37], 0, v[132:133]
	s_mov_b32 m0, s46
	s_nop 0
	global_load_lds_dwordx4 v[182:183], off
	s_setprio 0
	s_waitcnt vmcnt(8)
	s_waitcnt lgkmcnt(0)
	s_barrier
	s_setprio 1
	v_mfma_f32_16x16x32_bf16 v[126:129], v[142:145], v[202:205], v[126:129]
	v_mfma_f32_16x16x32_bf16 v[122:125], v[150:153], v[202:205], v[122:125]
	v_mfma_f32_16x16x32_bf16 v[110:113], v[142:145], v[210:213], v[110:113]
	v_mfma_f32_16x16x32_bf16 v[106:109], v[150:153], v[210:213], v[106:109]
	v_mfma_f32_16x16x32_bf16 v[92:95], v[142:145], v[218:221], v[92:95]
	v_mfma_f32_16x16x32_bf16 v[88:91], v[150:153], v[218:221], v[88:91]
	v_mfma_f32_16x16x32_bf16 v[76:79], v[142:145], v[226:229], v[76:79]
	v_mfma_f32_16x16x32_bf16 v[72:75], v[150:153], v[226:229], v[72:75]
	v_mfma_f32_16x16x32_bf16 v[126:129], v[146:149], v[206:209], v[126:129]
	v_mfma_f32_16x16x32_bf16 v[122:125], v[162:165], v[206:209], v[122:125]
	v_mfma_f32_16x16x32_bf16 v[110:113], v[146:149], v[214:217], v[110:113]
	v_mfma_f32_16x16x32_bf16 v[106:109], v[162:165], v[214:217], v[106:109]
	v_mfma_f32_16x16x32_bf16 v[92:95], v[146:149], v[222:225], v[92:95]
	v_mfma_f32_16x16x32_bf16 v[88:91], v[162:165], v[222:225], v[88:91]
	v_mfma_f32_16x16x32_bf16 v[76:79], v[146:149], v[230:233], v[76:79]
	v_mfma_f32_16x16x32_bf16 v[72:75], v[162:165], v[230:233], v[72:75]
	s_setprio 0
	s_setprio 1
	v_mfma_f32_16x16x32_bf16 v[118:121], v[186:189], v[202:205], v[118:121]
	v_mfma_f32_16x16x32_bf16 v[114:117], v[194:197], v[202:205], v[114:117]
	v_mfma_f32_16x16x32_bf16 v[102:105], v[186:189], v[210:213], v[102:105]
	v_mfma_f32_16x16x32_bf16 v[98:101], v[194:197], v[210:213], v[98:101]
	v_mfma_f32_16x16x32_bf16 v[84:87], v[186:189], v[218:221], v[84:87]
	v_mfma_f32_16x16x32_bf16 v[80:83], v[194:197], v[218:221], v[80:83]
	v_mfma_f32_16x16x32_bf16 v[68:71], v[186:189], v[226:229], v[68:71]
	v_mfma_f32_16x16x32_bf16 v[64:67], v[194:197], v[226:229], v[64:67]
	v_mfma_f32_16x16x32_bf16 v[118:121], v[190:193], v[206:209], v[118:121]
	v_mfma_f32_16x16x32_bf16 v[114:117], v[198:201], v[206:209], v[114:117]
	v_mfma_f32_16x16x32_bf16 v[102:105], v[190:193], v[214:217], v[102:105]
	v_mfma_f32_16x16x32_bf16 v[98:101], v[198:201], v[214:217], v[98:101]
	v_mfma_f32_16x16x32_bf16 v[84:87], v[190:193], v[222:225], v[84:87]
	v_mfma_f32_16x16x32_bf16 v[80:83], v[198:201], v[222:225], v[80:83]
	v_mfma_f32_16x16x32_bf16 v[68:71], v[190:193], v[230:233], v[68:71]
	v_mfma_f32_16x16x32_bf16 v[64:67], v[198:201], v[230:233], v[64:67]
	s_setprio 0
	s_barrier
	s_setprio 2
	s_add_i32 s36, s62, s42
	v_lshl_add_u64 v[154:155], v[154:155], 0, s[16:17]
	s_mov_b32 m0, s36
	ds_read_b128 v[202:205], v173 offset:49152
	ds_read_b128 v[206:209], v173 offset:50176
	ds_read_b128 v[210:213], v173 offset:51200
	ds_read_b128 v[214:217], v173 offset:52224
	ds_read_b128 v[218:221], v173 offset:53248
	ds_read_b128 v[222:225], v173 offset:54272
	ds_read_b128 v[226:229], v173 offset:55296
	ds_read_b128 v[230:233], v173 offset:56320
	global_load_lds_dwordx4 v[154:155], off
	s_add_i32 m0, s36, 0x2000
	s_add_u32 s14, s14, 0x40080
	v_lshl_add_u64 v[154:155], v[156:157], 0, s[16:17]
	s_addc_u32 s15, s15, 0
	s_add_i32 s36, s63, s42
	global_load_lds_dwordx4 v[154:155], off
	v_lshl_add_u64 v[154:155], s[14:15], 0, v[96:97]
	s_mov_b32 m0, s36
	s_nop 0
	global_load_lds_dwordx4 v[154:155], off
	v_lshl_add_u64 v[154:155], s[14:15], 0, v[130:131]
	s_add_i32 m0, s36, 0x2000
	s_nop 0
	global_load_lds_dwordx4 v[154:155], off
	v_lshl_add_u64 v[154:155], v[158:159], 0, s[16:17]
	s_mov_b32 m0, s52
	s_nop 0
	global_load_lds_dwordx4 v[154:155], off
	v_lshl_add_u64 v[154:155], v[166:167], 0, s[16:17]
	s_mov_b32 m0, s53
	s_nop 0
	global_load_lds_dwordx4 v[154:155], off
	s_setprio 0
	s_waitcnt vmcnt(8)
	s_waitcnt lgkmcnt(0)
	s_barrier
	s_setprio 1
	v_mfma_f32_16x16x32_bf16 v[60:63], v[142:145], v[202:205], v[60:63]
	v_mfma_f32_16x16x32_bf16 v[56:59], v[150:153], v[202:205], v[56:59]
	v_mfma_f32_16x16x32_bf16 v[44:47], v[142:145], v[210:213], v[44:47]
	v_mfma_f32_16x16x32_bf16 v[40:43], v[150:153], v[210:213], v[40:43]
	v_mfma_f32_16x16x32_bf16 v[28:31], v[142:145], v[218:221], v[28:31]
	v_mfma_f32_16x16x32_bf16 v[24:27], v[150:153], v[218:221], v[24:27]
	v_mfma_f32_16x16x32_bf16 v[12:15], v[142:145], v[226:229], v[12:15]
	v_mfma_f32_16x16x32_bf16 v[8:11], v[150:153], v[226:229], v[8:11]
	v_mfma_f32_16x16x32_bf16 v[60:63], v[146:149], v[206:209], v[60:63]
	v_mfma_f32_16x16x32_bf16 v[56:59], v[162:165], v[206:209], v[56:59]
	v_mfma_f32_16x16x32_bf16 v[44:47], v[146:149], v[214:217], v[44:47]
	v_mfma_f32_16x16x32_bf16 v[40:43], v[162:165], v[214:217], v[40:43]
	v_mfma_f32_16x16x32_bf16 v[28:31], v[146:149], v[222:225], v[28:31]
	v_mfma_f32_16x16x32_bf16 v[24:27], v[162:165], v[222:225], v[24:27]
	v_mfma_f32_16x16x32_bf16 v[12:15], v[146:149], v[230:233], v[12:15]
	v_mfma_f32_16x16x32_bf16 v[8:11], v[162:165], v[230:233], v[8:11]
	s_setprio 0
	s_setprio 1
	v_mfma_f32_16x16x32_bf16 v[52:55], v[186:189], v[202:205], v[52:55]
	v_mfma_f32_16x16x32_bf16 v[48:51], v[194:197], v[202:205], v[48:51]
	v_mfma_f32_16x16x32_bf16 v[36:39], v[186:189], v[210:213], v[36:39]
	v_mfma_f32_16x16x32_bf16 v[32:35], v[194:197], v[210:213], v[32:35]
	v_mfma_f32_16x16x32_bf16 v[20:23], v[186:189], v[218:221], v[20:23]
	v_mfma_f32_16x16x32_bf16 v[16:19], v[194:197], v[218:221], v[16:19]
	v_mfma_f32_16x16x32_bf16 v[4:7], v[186:189], v[226:229], v[4:7]
	v_mfma_f32_16x16x32_bf16 v[0:3], v[194:197], v[226:229], v[0:3]
	v_mfma_f32_16x16x32_bf16 v[52:55], v[190:193], v[206:209], v[52:55]
	v_mfma_f32_16x16x32_bf16 v[48:51], v[198:201], v[206:209], v[48:51]
	v_mfma_f32_16x16x32_bf16 v[36:39], v[190:193], v[214:217], v[36:39]
	v_mfma_f32_16x16x32_bf16 v[32:35], v[198:201], v[214:217], v[32:35]
	v_mfma_f32_16x16x32_bf16 v[20:23], v[190:193], v[222:225], v[20:23]
	v_mfma_f32_16x16x32_bf16 v[16:19], v[198:201], v[222:225], v[16:19]
	v_mfma_f32_16x16x32_bf16 v[4:7], v[190:193], v[230:233], v[4:7]
	v_mfma_f32_16x16x32_bf16 v[0:3], v[198:201], v[230:233], v[0:3]
	s_add_i32 s61, s61, 2
	s_add_u32 s4, s4, 0x100
	s_addc_u32 s5, s5, 0
	s_add_u32 s59, s59, 0x100
	s_addc_u32 s60, s60, 0
	s_setprio 0
	s_barrier
	s_setprio 2
	s_cmp_gt_u32 s61, 13
	s_cbranch_scc0 .LBB0_427
	s_and_b64 vcc, exec, s[24:25]
	s_cbranch_vccz .LBB0_430
	s_barrier

.LBB0_449:
	s_add_i32 s60, 0, 0x10000
	v_add_u32_e32 v96, s60, v151
	s_add_i32 s62, 0, 0x14000
	ds_read_b128 v[144:147], v96
	ds_read_b128 v[164:167], v96 offset:1024
	ds_read_b128 v[168:171], v96 offset:2048
	ds_read_b128 v[186:189], v96 offset:3072
	v_add_u32_e32 v96, s62, v151
	ds_read_b128 v[190:193], v96
	ds_read_b128 v[194:197], v96 offset:1024
	ds_read_b128 v[198:201], v96 offset:2048
	ds_read_b128 v[202:205], v96 offset:3072
	s_add_u32 s30, s14, 0xfffc0080
	s_addc_u32 s31, s15, -1
	s_cmp_eq_u32 s59, 12
	s_cselect_b32 s35, s25, s31
	s_cselect_b32 s34, s55, s30
	s_cselect_b32 s31, s13, s58
	s_cselect_b32 s30, s56, s57
	v_lshl_add_u64 v[148:149], s[14:15], 0, v[140:141]
	s_add_i32 m0, s41, 0xc000
	ds_read_b128 v[206:209], v163
	ds_read_b128 v[210:213], v163 offset:1024
	ds_read_b128 v[214:217], v163 offset:2048
	ds_read_b128 v[218:221], v163 offset:3072
	ds_read_b128 v[222:225], v163 offset:4096
	ds_read_b128 v[226:229], v163 offset:5120
	ds_read_b128 v[230:233], v163 offset:6144
	ds_read_b128 v[242:245], v163 offset:7168
	global_load_lds_dwordx4 v[148:149], off
	v_lshl_add_u64 v[148:149], s[14:15], 0, v[142:143]
	s_add_i32 m0, s41, 0xe000
	s_nop 0
	global_load_lds_dwordx4 v[148:149], off
	s_setprio 0
	s_waitcnt vmcnt(8)
	s_waitcnt lgkmcnt(0)
	s_barrier
	s_setprio 1
	v_mfma_f32_16x16x32_bf16 v[126:129], v[144:147], v[206:209], v[126:129]
	v_mfma_f32_16x16x32_bf16 v[122:125], v[168:171], v[206:209], v[122:125]
	v_mfma_f32_16x16x32_bf16 v[110:113], v[144:147], v[214:217], v[110:113]
	v_mfma_f32_16x16x32_bf16 v[106:109], v[168:171], v[214:217], v[106:109]
	v_mfma_f32_16x16x32_bf16 v[92:95], v[144:147], v[222:225], v[92:95]
	v_mfma_f32_16x16x32_bf16 v[88:91], v[168:171], v[222:225], v[88:91]
	v_mfma_f32_16x16x32_bf16 v[76:79], v[144:147], v[230:233], v[76:79]
	v_mfma_f32_16x16x32_bf16 v[72:75], v[168:171], v[230:233], v[72:75]
	v_mfma_f32_16x16x32_bf16 v[126:129], v[164:167], v[210:213], v[126:129]
	v_mfma_f32_16x16x32_bf16 v[122:125], v[186:189], v[210:213], v[122:125]
	v_mfma_f32_16x16x32_bf16 v[110:113], v[164:167], v[218:221], v[110:113]
	v_mfma_f32_16x16x32_bf16 v[106:109], v[186:189], v[218:221], v[106:109]
	v_mfma_f32_16x16x32_bf16 v[92:95], v[164:167], v[226:229], v[92:95]
	v_mfma_f32_16x16x32_bf16 v[88:91], v[186:189], v[226:229], v[88:91]
	v_mfma_f32_16x16x32_bf16 v[76:79], v[164:167], v[242:245], v[76:79]
	v_mfma_f32_16x16x32_bf16 v[72:75], v[186:189], v[242:245], v[72:75]
	s_setprio 0
	s_setprio 1
	v_mfma_f32_16x16x32_bf16 v[118:121], v[190:193], v[206:209], v[118:121]
	v_mfma_f32_16x16x32_bf16 v[114:117], v[198:201], v[206:209], v[114:117]
	v_mfma_f32_16x16x32_bf16 v[102:105], v[190:193], v[214:217], v[102:105]
	v_mfma_f32_16x16x32_bf16 v[98:101], v[198:201], v[214:217], v[98:101]
	v_mfma_f32_16x16x32_bf16 v[84:87], v[190:193], v[222:225], v[84:87]
	v_mfma_f32_16x16x32_bf16 v[80:83], v[198:201], v[222:225], v[80:83]
	v_mfma_f32_16x16x32_bf16 v[68:71], v[190:193], v[230:233], v[68:71]
	v_mfma_f32_16x16x32_bf16 v[64:67], v[198:201], v[230:233], v[64:67]
	v_mfma_f32_16x16x32_bf16 v[118:121], v[194:197], v[210:213], v[118:121]
	v_mfma_f32_16x16x32_bf16 v[114:117], v[202:205], v[210:213], v[114:117]
	v_mfma_f32_16x16x32_bf16 v[102:105], v[194:197], v[218:221], v[102:105]
	v_mfma_f32_16x16x32_bf16 v[98:101], v[202:205], v[218:221], v[98:101]
	v_mfma_f32_16x16x32_bf16 v[84:87], v[194:197], v[226:229], v[84:87]
	v_mfma_f32_16x16x32_bf16 v[80:83], v[202:205], v[226:229], v[80:83]
	v_mfma_f32_16x16x32_bf16 v[68:71], v[194:197], v[242:245], v[68:71]
	v_mfma_f32_16x16x32_bf16 v[64:67], v[202:205], v[242:245], v[64:67]
	s_setprio 0
	s_barrier
	s_setprio 2
	s_add_i32 s60, s60, s40
	v_lshl_add_u64 v[148:149], s[30:31], 0, v[134:135]
	s_mov_b32 m0, s60
	ds_read_b128 v[206:209], v163 offset:16384
	ds_read_b128 v[210:213], v163 offset:17408
	ds_read_b128 v[214:217], v163 offset:18432
	ds_read_b128 v[218:221], v163 offset:19456
	ds_read_b128 v[222:225], v163 offset:20480
	ds_read_b128 v[226:229], v163 offset:21504
	ds_read_b128 v[230:233], v163 offset:22528
	ds_read_b128 v[242:245], v163 offset:23552
	global_load_lds_dwordx4 v[148:149], off
	s_add_i32 m0, s60, 0x2000
	s_add_u32 s60, s30, 0x40000
	v_lshl_add_u64 v[154:155], s[30:31], 0, v[130:131]
	s_addc_u32 s61, s31, 0
	s_add_i32 s62, s62, s40
	global_load_lds_dwordx4 v[154:155], off
	v_lshl_add_u64 v[156:157], s[60:61], 0, v[134:135]
	s_mov_b32 m0, s62
	v_lshl_add_u64 v[158:159], s[34:35], 0, v[132:133]
	global_load_lds_dwordx4 v[156:157], off
	v_lshl_add_u64 v[156:157], s[60:61], 0, v[130:131]
	s_add_i32 m0, s62, 0x2000
	s_nop 0
	global_load_lds_dwordx4 v[156:157], off
	v_lshl_add_u64 v[156:157], s[34:35], 0, v[136:137]
	s_mov_b32 m0, s41
	s_nop 0
	global_load_lds_dwordx4 v[156:157], off
	s_mov_b32 m0, s42
	s_nop 0
	global_load_lds_dwordx4 v[158:159], off
	s_setprio 0
	s_waitcnt vmcnt(8)
	s_waitcnt lgkmcnt(0)
	s_barrier
	s_setprio 1
	v_mfma_f32_16x16x32_bf16 v[60:63], v[144:147], v[206:209], v[60:63]
	v_mfma_f32_16x16x32_bf16 v[56:59], v[168:171], v[206:209], v[56:59]
	v_mfma_f32_16x16x32_bf16 v[44:47], v[144:147], v[214:217], v[44:47]
	v_mfma_f32_16x16x32_bf16 v[40:43], v[168:171], v[214:217], v[40:43]
	v_mfma_f32_16x16x32_bf16 v[28:31], v[144:147], v[222:225], v[28:31]
	v_mfma_f32_16x16x32_bf16 v[24:27], v[168:171], v[222:225], v[24:27]
	v_mfma_f32_16x16x32_bf16 v[12:15], v[144:147], v[230:233], v[12:15]
	v_mfma_f32_16x16x32_bf16 v[8:11], v[168:171], v[230:233], v[8:11]
	v_mfma_f32_16x16x32_bf16 v[60:63], v[164:167], v[210:213], v[60:63]
	v_mfma_f32_16x16x32_bf16 v[56:59], v[186:189], v[210:213], v[56:59]
	v_mfma_f32_16x16x32_bf16 v[44:47], v[164:167], v[218:221], v[44:47]
	v_mfma_f32_16x16x32_bf16 v[40:43], v[186:189], v[218:221], v[40:43]
	v_mfma_f32_16x16x32_bf16 v[28:31], v[164:167], v[226:229], v[28:31]
	v_mfma_f32_16x16x32_bf16 v[24:27], v[186:189], v[226:229], v[24:27]
	v_mfma_f32_16x16x32_bf16 v[12:15], v[164:167], v[242:245], v[12:15]
	v_mfma_f32_16x16x32_bf16 v[8:11], v[186:189], v[242:245], v[8:11]
	s_setprio 0
	s_setprio 1
	v_mfma_f32_16x16x32_bf16 v[52:55], v[190:193], v[206:209], v[52:55]
	v_mfma_f32_16x16x32_bf16 v[48:51], v[198:201], v[206:209], v[48:51]
	v_mfma_f32_16x16x32_bf16 v[36:39], v[190:193], v[214:217], v[36:39]
	v_mfma_f32_16x16x32_bf16 v[32:35], v[198:201], v[214:217], v[32:35]
	v_mfma_f32_16x16x32_bf16 v[20:23], v[190:193], v[222:225], v[20:23]
	v_mfma_f32_16x16x32_bf16 v[16:19], v[198:201], v[222:225], v[16:19]
	v_mfma_f32_16x16x32_bf16 v[4:7], v[190:193], v[230:233], v[4:7]
	v_mfma_f32_16x16x32_bf16 v[0:3], v[198:201], v[230:233], v[0:3]
	v_mfma_f32_16x16x32_bf16 v[52:55], v[194:197], v[210:213], v[52:55]
	v_mfma_f32_16x16x32_bf16 v[48:51], v[202:205], v[210:213], v[48:51]
	v_mfma_f32_16x16x32_bf16 v[36:39], v[194:197], v[218:221], v[36:39]
	v_mfma_f32_16x16x32_bf16 v[32:35], v[202:205], v[218:221], v[32:35]
	v_mfma_f32_16x16x32_bf16 v[20:23], v[194:197], v[226:229], v[20:23]
	v_mfma_f32_16x16x32_bf16 v[16:19], v[202:205], v[226:229], v[16:19]
	v_mfma_f32_16x16x32_bf16 v[4:7], v[194:197], v[242:245], v[4:7]
	v_mfma_f32_16x16x32_bf16 v[0:3], v[202:205], v[242:245], v[0:3]
	s_setprio 0
	s_barrier
	s_setprio 2
	s_add_i32 s60, 0, 0x18000
	v_add_u32_e32 v96, s60, v151
	s_add_i32 s61, 0, 0x1c000
	ds_read_b128 v[144:147], v96
	ds_read_b128 v[164:167], v96 offset:1024
	ds_read_b128 v[168:171], v96 offset:2048
	ds_read_b128 v[186:189], v96 offset:3072
	v_add_u32_e32 v96, s61, v151
	ds_read_b128 v[190:193], v96
	ds_read_b128 v[194:197], v96 offset:1024
	ds_read_b128 v[198:201], v96 offset:2048
	ds_read_b128 v[202:205], v96 offset:3072
	s_add_u32 s34, s34, 0x40000
	s_addc_u32 s35, s35, 0
	s_mov_b32 m0, s43
	v_lshl_add_u64 v[172:173], s[34:35], 0, v[136:137]
	ds_read_b128 v[206:209], v163 offset:32768
	ds_read_b128 v[210:213], v163 offset:33792
	ds_read_b128 v[214:217], v163 offset:34816
	ds_read_b128 v[218:221], v163 offset:35840
	ds_read_b128 v[222:225], v163 offset:36864
	ds_read_b128 v[226:229], v163 offset:37888
	ds_read_b128 v[230:233], v163 offset:38912
	ds_read_b128 v[242:245], v163 offset:39936
	global_load_lds_dwordx4 v[172:173], off
	v_lshl_add_u64 v[172:173], s[34:35], 0, v[132:133]
	s_mov_b32 m0, s44
	s_nop 0
	global_load_lds_dwordx4 v[172:173], off
	s_setprio 0
	s_waitcnt vmcnt(8)
	s_waitcnt lgkmcnt(0)
	s_barrier
	s_setprio 1
	v_mfma_f32_16x16x32_bf16 v[126:129], v[144:147], v[206:209], v[126:129]
	v_mfma_f32_16x16x32_bf16 v[122:125], v[168:171], v[206:209], v[122:125]
	v_mfma_f32_16x16x32_bf16 v[110:113], v[144:147], v[214:217], v[110:113]
	v_mfma_f32_16x16x32_bf16 v[106:109], v[168:171], v[214:217], v[106:109]
	v_mfma_f32_16x16x32_bf16 v[92:95], v[144:147], v[222:225], v[92:95]
	v_mfma_f32_16x16x32_bf16 v[88:91], v[168:171], v[222:225], v[88:91]
	v_mfma_f32_16x16x32_bf16 v[76:79], v[144:147], v[230:233], v[76:79]
	v_mfma_f32_16x16x32_bf16 v[72:75], v[168:171], v[230:233], v[72:75]
	v_mfma_f32_16x16x32_bf16 v[126:129], v[164:167], v[210:213], v[126:129]
	v_mfma_f32_16x16x32_bf16 v[122:125], v[186:189], v[210:213], v[122:125]
	v_mfma_f32_16x16x32_bf16 v[110:113], v[164:167], v[218:221], v[110:113]
	v_mfma_f32_16x16x32_bf16 v[106:109], v[186:189], v[218:221], v[106:109]
	v_mfma_f32_16x16x32_bf16 v[92:95], v[164:167], v[226:229], v[92:95]
	v_mfma_f32_16x16x32_bf16 v[88:91], v[186:189], v[226:229], v[88:91]
	v_mfma_f32_16x16x32_bf16 v[76:79], v[164:167], v[242:245], v[76:79]
	v_mfma_f32_16x16x32_bf16 v[72:75], v[186:189], v[242:245], v[72:75]
	s_setprio 0
	s_setprio 1
	v_mfma_f32_16x16x32_bf16 v[118:121], v[190:193], v[206:209], v[118:121]
	v_mfma_f32_16x16x32_bf16 v[114:117], v[198:201], v[206:209], v[114:117]
	v_mfma_f32_16x16x32_bf16 v[102:105], v[190:193], v[214:217], v[102:105]
	v_mfma_f32_16x16x32_bf16 v[98:101], v[198:201], v[214:217], v[98:101]
	v_mfma_f32_16x16x32_bf16 v[84:87], v[190:193], v[222:225], v[84:87]
	v_mfma_f32_16x16x32_bf16 v[80:83], v[198:201], v[222:225], v[80:83]
	v_mfma_f32_16x16x32_bf16 v[68:71], v[190:193], v[230:233], v[68:71]
	v_mfma_f32_16x16x32_bf16 v[64:67], v[198:201], v[230:233], v[64:67]
	v_mfma_f32_16x16x32_bf16 v[118:121], v[194:197], v[210:213], v[118:121]
	v_mfma_f32_16x16x32_bf16 v[114:117], v[202:205], v[210:213], v[114:117]
	v_mfma_f32_16x16x32_bf16 v[102:105], v[194:197], v[218:221], v[102:105]
	v_mfma_f32_16x16x32_bf16 v[98:101], v[202:205], v[218:221], v[98:101]
	v_mfma_f32_16x16x32_bf16 v[84:87], v[194:197], v[226:229], v[84:87]
	v_mfma_f32_16x16x32_bf16 v[80:83], v[202:205], v[226:229], v[80:83]
	v_mfma_f32_16x16x32_bf16 v[68:71], v[194:197], v[242:245], v[68:71]
	v_mfma_f32_16x16x32_bf16 v[64:67], v[202:205], v[242:245], v[64:67]
	s_setprio 0
	s_barrier
	s_setprio 2
	s_add_i32 s34, s60, s40
	v_lshl_add_u64 v[148:149], v[148:149], 0, s[16:17]
	s_mov_b32 m0, s34
	ds_read_b128 v[206:209], v163 offset:49152
	ds_read_b128 v[210:213], v163 offset:50176
	ds_read_b128 v[214:217], v163 offset:51200
	ds_read_b128 v[218:221], v163 offset:52224
	ds_read_b128 v[222:225], v163 offset:53248
	ds_read_b128 v[226:229], v163 offset:54272
	ds_read_b128 v[230:233], v163 offset:55296
	ds_read_b128 v[242:245], v163 offset:56320
	global_load_lds_dwordx4 v[148:149], off
	s_add_i32 m0, s34, 0x2000
	s_add_u32 s30, s30, 0x40080
	v_lshl_add_u64 v[148:149], v[154:155], 0, s[16:17]
	s_addc_u32 s31, s31, 0
	s_add_i32 s34, s61, s40
	global_load_lds_dwordx4 v[148:149], off
	v_lshl_add_u64 v[148:149], s[30:31], 0, v[134:135]
	s_mov_b32 m0, s34
	s_nop 0
	global_load_lds_dwordx4 v[148:149], off
	v_lshl_add_u64 v[148:149], s[30:31], 0, v[130:131]
	s_add_i32 m0, s34, 0x2000
	s_nop 0
	global_load_lds_dwordx4 v[148:149], off
	v_lshl_add_u64 v[148:149], v[156:157], 0, s[16:17]
	s_mov_b32 m0, s49
	s_nop 0
	global_load_lds_dwordx4 v[148:149], off
	v_lshl_add_u64 v[148:149], v[158:159], 0, s[16:17]
	s_mov_b32 m0, s50
	s_nop 0
	global_load_lds_dwordx4 v[148:149], off
	s_setprio 0
	s_waitcnt vmcnt(8)
	s_waitcnt lgkmcnt(0)
	s_barrier
	s_setprio 1
	v_mfma_f32_16x16x32_bf16 v[60:63], v[144:147], v[206:209], v[60:63]
	v_mfma_f32_16x16x32_bf16 v[56:59], v[168:171], v[206:209], v[56:59]
	v_mfma_f32_16x16x32_bf16 v[44:47], v[144:147], v[214:217], v[44:47]
	v_mfma_f32_16x16x32_bf16 v[40:43], v[168:171], v[214:217], v[40:43]
	v_mfma_f32_16x16x32_bf16 v[28:31], v[144:147], v[222:225], v[28:31]
	v_mfma_f32_16x16x32_bf16 v[24:27], v[168:171], v[222:225], v[24:27]
	v_mfma_f32_16x16x32_bf16 v[12:15], v[144:147], v[230:233], v[12:15]
	v_mfma_f32_16x16x32_bf16 v[8:11], v[168:171], v[230:233], v[8:11]
	v_mfma_f32_16x16x32_bf16 v[60:63], v[164:167], v[210:213], v[60:63]
	v_mfma_f32_16x16x32_bf16 v[56:59], v[186:189], v[210:213], v[56:59]
	v_mfma_f32_16x16x32_bf16 v[44:47], v[164:167], v[218:221], v[44:47]
	v_mfma_f32_16x16x32_bf16 v[40:43], v[186:189], v[218:221], v[40:43]
	v_mfma_f32_16x16x32_bf16 v[28:31], v[164:167], v[226:229], v[28:31]
	v_mfma_f32_16x16x32_bf16 v[24:27], v[186:189], v[226:229], v[24:27]
	v_mfma_f32_16x16x32_bf16 v[12:15], v[164:167], v[242:245], v[12:15]
	v_mfma_f32_16x16x32_bf16 v[8:11], v[186:189], v[242:245], v[8:11]
	s_setprio 0
	s_setprio 1
	v_mfma_f32_16x16x32_bf16 v[52:55], v[190:193], v[206:209], v[52:55]
	v_mfma_f32_16x16x32_bf16 v[48:51], v[198:201], v[206:209], v[48:51]
	v_mfma_f32_16x16x32_bf16 v[36:39], v[190:193], v[214:217], v[36:39]
	v_mfma_f32_16x16x32_bf16 v[32:35], v[198:201], v[214:217], v[32:35]
	v_mfma_f32_16x16x32_bf16 v[20:23], v[190:193], v[222:225], v[20:23]
	v_mfma_f32_16x16x32_bf16 v[16:19], v[198:201], v[222:225], v[16:19]
	v_mfma_f32_16x16x32_bf16 v[4:7], v[190:193], v[230:233], v[4:7]
	v_mfma_f32_16x16x32_bf16 v[0:3], v[198:201], v[230:233], v[0:3]
	v_mfma_f32_16x16x32_bf16 v[52:55], v[194:197], v[210:213], v[52:55]
	v_mfma_f32_16x16x32_bf16 v[48:51], v[202:205], v[210:213], v[48:51]
	v_mfma_f32_16x16x32_bf16 v[36:39], v[194:197], v[218:221], v[36:39]
	v_mfma_f32_16x16x32_bf16 v[32:35], v[202:205], v[218:221], v[32:35]
	v_mfma_f32_16x16x32_bf16 v[20:23], v[194:197], v[226:229], v[20:23]
	v_mfma_f32_16x16x32_bf16 v[16:19], v[202:205], v[226:229], v[16:19]
	v_mfma_f32_16x16x32_bf16 v[4:7], v[194:197], v[242:245], v[4:7]
	v_mfma_f32_16x16x32_bf16 v[0:3], v[202:205], v[242:245], v[0:3]
	s_add_i32 s59, s59, 2
	s_add_u32 s14, s14, 0x100
	s_addc_u32 s15, s15, 0
	s_add_u32 s57, s57, 0x100
	s_addc_u32 s58, s58, 0
	s_setprio 0
	s_barrier
	s_setprio 2
	s_cmp_gt_u32 s59, 13
	s_cbranch_scc0 .LBB0_449
	s_and_b64 vcc, exec, s[18:19]
	s_cbranch_vccz .LBB0_454
	s_barrier
	v_lshl_add_u32 v146, s54, 8, v150
	s_cmp_gt_i32 s53, 7
	s_mov_b64 s[14:15], -1
	s_cbranch_scc1 .LBB0_455

.LBB0_490:
	s_add_i32 s66, s6, 2
	s_add_u32 s67, s4, 0x80
	s_addc_u32 s7, s5, 0
	s_add_i32 s70, 0, 0x10000
	s_cmp_eq_u32 s60, s6
	s_cselect_b32 s7, s43, s7
	s_cselect_b32 s6, s42, s67
	v_add_u32_e32 v148, s70, v151
	s_cselect_b32 s69, s45, s15
	s_cselect_b32 s68, s44, s14
	s_add_i32 s67, 0, 0x14000
	ds_read_b128 v[140:143], v148
	ds_read_b128 v[144:147], v148 offset:1024
	ds_read_b128 v[162:165], v148 offset:2048
	ds_read_b128 v[166:169], v148 offset:3072
	v_add_u32_e32 v148, s67, v151
	ds_read_b128 v[170:173], v148
	ds_read_b128 v[186:189], v148 offset:1024
	ds_read_b128 v[190:193], v148 offset:2048
	ds_read_b128 v[194:197], v148 offset:3072
	v_lshl_add_u64 v[148:149], s[4:5], 0, v[136:137]
	s_add_i32 m0, s52, 0xc000
	ds_read_b128 v[198:201], v153
	ds_read_b128 v[202:205], v153 offset:1024
	ds_read_b128 v[206:209], v153 offset:2048
	ds_read_b128 v[210:213], v153 offset:3072
	ds_read_b128 v[214:217], v153 offset:4096
	ds_read_b128 v[218:221], v153 offset:5120
	ds_read_b128 v[222:225], v153 offset:6144
	ds_read_b128 v[226:229], v153 offset:7168
	global_load_lds_dwordx4 v[148:149], off
	v_lshl_add_u64 v[148:149], s[4:5], 0, v[138:139]
	s_add_i32 m0, s52, 0xe000
	s_nop 0
	global_load_lds_dwordx4 v[148:149], off
	s_setprio 0
	s_waitcnt vmcnt(8)
	s_waitcnt lgkmcnt(0)
	s_barrier
	s_setprio 1
	v_mfma_f32_16x16x32_bf16 v[126:129], v[140:143], v[198:201], v[126:129]
	v_mfma_f32_16x16x32_bf16 v[122:125], v[162:165], v[198:201], v[122:125]
	v_mfma_f32_16x16x32_bf16 v[110:113], v[140:143], v[206:209], v[110:113]
	v_mfma_f32_16x16x32_bf16 v[106:109], v[162:165], v[206:209], v[106:109]
	v_mfma_f32_16x16x32_bf16 v[92:95], v[140:143], v[214:217], v[92:95]
	v_mfma_f32_16x16x32_bf16 v[88:91], v[162:165], v[214:217], v[88:91]
	v_mfma_f32_16x16x32_bf16 v[76:79], v[140:143], v[222:225], v[76:79]
	v_mfma_f32_16x16x32_bf16 v[72:75], v[162:165], v[222:225], v[72:75]
	v_mfma_f32_16x16x32_bf16 v[126:129], v[144:147], v[202:205], v[126:129]
	v_mfma_f32_16x16x32_bf16 v[122:125], v[166:169], v[202:205], v[122:125]
	v_mfma_f32_16x16x32_bf16 v[110:113], v[144:147], v[210:213], v[110:113]
	v_mfma_f32_16x16x32_bf16 v[106:109], v[166:169], v[210:213], v[106:109]
	v_mfma_f32_16x16x32_bf16 v[92:95], v[144:147], v[218:221], v[92:95]
	v_mfma_f32_16x16x32_bf16 v[88:91], v[166:169], v[218:221], v[88:91]
	v_mfma_f32_16x16x32_bf16 v[76:79], v[144:147], v[226:229], v[76:79]
	v_mfma_f32_16x16x32_bf16 v[72:75], v[166:169], v[226:229], v[72:75]
	s_setprio 0
	s_setprio 1
	v_mfma_f32_16x16x32_bf16 v[118:121], v[170:173], v[198:201], v[118:121]
	v_mfma_f32_16x16x32_bf16 v[114:117], v[190:193], v[198:201], v[114:117]
	v_mfma_f32_16x16x32_bf16 v[102:105], v[170:173], v[206:209], v[102:105]
	v_mfma_f32_16x16x32_bf16 v[98:101], v[190:193], v[206:209], v[98:101]
	v_mfma_f32_16x16x32_bf16 v[84:87], v[170:173], v[214:217], v[84:87]
	v_mfma_f32_16x16x32_bf16 v[80:83], v[190:193], v[214:217], v[80:83]
	v_mfma_f32_16x16x32_bf16 v[68:71], v[170:173], v[222:225], v[68:71]
	v_mfma_f32_16x16x32_bf16 v[64:67], v[190:193], v[222:225], v[64:67]
	v_mfma_f32_16x16x32_bf16 v[118:121], v[186:189], v[202:205], v[118:121]
	v_mfma_f32_16x16x32_bf16 v[114:117], v[194:197], v[202:205], v[114:117]
	v_mfma_f32_16x16x32_bf16 v[102:105], v[186:189], v[210:213], v[102:105]
	v_mfma_f32_16x16x32_bf16 v[98:101], v[194:197], v[210:213], v[98:101]
	v_mfma_f32_16x16x32_bf16 v[84:87], v[186:189], v[218:221], v[84:87]
	v_mfma_f32_16x16x32_bf16 v[80:83], v[194:197], v[218:221], v[80:83]
	v_mfma_f32_16x16x32_bf16 v[68:71], v[186:189], v[226:229], v[68:71]
	v_mfma_f32_16x16x32_bf16 v[64:67], v[194:197], v[226:229], v[64:67]
	s_setprio 0
	s_barrier
	s_setprio 2
	s_add_i32 s70, s70, s51
	v_lshl_add_u64 v[148:149], s[68:69], 0, v[96:97]
	s_mov_b32 m0, s70
	ds_read_b128 v[198:201], v153 offset:16384
	ds_read_b128 v[202:205], v153 offset:17408
	ds_read_b128 v[206:209], v153 offset:18432
	ds_read_b128 v[210:213], v153 offset:19456
	ds_read_b128 v[214:217], v153 offset:20480
	ds_read_b128 v[218:221], v153 offset:21504
	ds_read_b128 v[222:225], v153 offset:22528
	ds_read_b128 v[226:229], v153 offset:23552
	global_load_lds_dwordx4 v[148:149], off
	s_add_i32 m0, s70, 0x2000
	v_lshl_add_u64 v[154:155], s[68:69], 0, v[130:131]
	s_add_u32 s68, s68, s46
	s_addc_u32 s69, s69, 0
	s_add_i32 s67, s67, s51
	global_load_lds_dwordx4 v[154:155], off
	v_lshl_add_u64 v[156:157], s[68:69], 0, v[96:97]
	s_mov_b32 m0, s67
	v_lshl_add_u64 v[158:159], s[68:69], 0, v[130:131]
	global_load_lds_dwordx4 v[156:157], off
	s_add_i32 m0, s67, 0x2000
	v_lshl_add_u64 v[182:183], s[6:7], 0, v[134:135]
	global_load_lds_dwordx4 v[158:159], off
	s_mov_b32 m0, s52
	v_lshl_add_u64 v[184:185], s[6:7], 0, v[132:133]
	global_load_lds_dwordx4 v[182:183], off
	s_mov_b32 m0, s53
	s_nop 0
	global_load_lds_dwordx4 v[184:185], off
	s_setprio 0
	s_waitcnt vmcnt(8)
	s_waitcnt lgkmcnt(0)
	s_barrier
	s_setprio 1
	v_mfma_f32_16x16x32_bf16 v[60:63], v[140:143], v[198:201], v[60:63]
	v_mfma_f32_16x16x32_bf16 v[56:59], v[162:165], v[198:201], v[56:59]
	v_mfma_f32_16x16x32_bf16 v[44:47], v[140:143], v[206:209], v[44:47]
	v_mfma_f32_16x16x32_bf16 v[40:43], v[162:165], v[206:209], v[40:43]
	v_mfma_f32_16x16x32_bf16 v[28:31], v[140:143], v[214:217], v[28:31]
	v_mfma_f32_16x16x32_bf16 v[24:27], v[162:165], v[214:217], v[24:27]
	v_mfma_f32_16x16x32_bf16 v[12:15], v[140:143], v[222:225], v[12:15]
	v_mfma_f32_16x16x32_bf16 v[8:11], v[162:165], v[222:225], v[8:11]
	v_mfma_f32_16x16x32_bf16 v[60:63], v[144:147], v[202:205], v[60:63]
	v_mfma_f32_16x16x32_bf16 v[56:59], v[166:169], v[202:205], v[56:59]
	v_mfma_f32_16x16x32_bf16 v[44:47], v[144:147], v[210:213], v[44:47]
	v_mfma_f32_16x16x32_bf16 v[40:43], v[166:169], v[210:213], v[40:43]
	v_mfma_f32_16x16x32_bf16 v[28:31], v[144:147], v[218:221], v[28:31]
	v_mfma_f32_16x16x32_bf16 v[24:27], v[166:169], v[218:221], v[24:27]
	v_mfma_f32_16x16x32_bf16 v[12:15], v[144:147], v[226:229], v[12:15]
	v_mfma_f32_16x16x32_bf16 v[8:11], v[166:169], v[226:229], v[8:11]
	s_setprio 0
	s_setprio 1
	v_mfma_f32_16x16x32_bf16 v[52:55], v[170:173], v[198:201], v[52:55]
	v_mfma_f32_16x16x32_bf16 v[48:51], v[190:193], v[198:201], v[48:51]
	v_mfma_f32_16x16x32_bf16 v[36:39], v[170:173], v[206:209], v[36:39]
	v_mfma_f32_16x16x32_bf16 v[32:35], v[190:193], v[206:209], v[32:35]
	v_mfma_f32_16x16x32_bf16 v[20:23], v[170:173], v[214:217], v[20:23]
	v_mfma_f32_16x16x32_bf16 v[16:19], v[190:193], v[214:217], v[16:19]
	v_mfma_f32_16x16x32_bf16 v[4:7], v[170:173], v[222:225], v[4:7]
	v_mfma_f32_16x16x32_bf16 v[0:3], v[190:193], v[222:225], v[0:3]
	v_mfma_f32_16x16x32_bf16 v[52:55], v[186:189], v[202:205], v[52:55]
	v_mfma_f32_16x16x32_bf16 v[48:51], v[194:197], v[202:205], v[48:51]
	v_mfma_f32_16x16x32_bf16 v[36:39], v[186:189], v[210:213], v[36:39]
	v_mfma_f32_16x16x32_bf16 v[32:35], v[194:197], v[210:213], v[32:35]
	v_mfma_f32_16x16x32_bf16 v[20:23], v[186:189], v[218:221], v[20:23]
	v_mfma_f32_16x16x32_bf16 v[16:19], v[194:197], v[218:221], v[16:19]
	v_mfma_f32_16x16x32_bf16 v[4:7], v[186:189], v[226:229], v[4:7]
	v_mfma_f32_16x16x32_bf16 v[0:3], v[194:197], v[226:229], v[0:3]
	s_setprio 0
	s_barrier
	s_setprio 2
	s_add_i32 s67, 0, 0x18000
	s_add_i32 s68, 0, 0x1c000
	v_add_u32_e32 v166, s67, v151
	v_add_u32_e32 v194, s68, v151
	ds_read_b128 v[140:143], v166
	ds_read_b128 v[144:147], v166 offset:1024
	ds_read_b128 v[162:165], v166 offset:2048
	ds_read_b128 v[166:169], v166 offset:3072
	ds_read_b128 v[170:173], v194
	ds_read_b128 v[186:189], v194 offset:1024
	ds_read_b128 v[190:193], v194 offset:2048
	ds_read_b128 v[194:197], v194 offset:3072
	s_add_u32 s6, s6, s46
	s_addc_u32 s7, s7, 0
	s_mov_b32 m0, s54
	v_lshl_add_u64 v[230:231], s[6:7], 0, v[134:135]
	ds_read_b128 v[198:201], v153 offset:32768
	ds_read_b128 v[202:205], v153 offset:33792
	ds_read_b128 v[206:209], v153 offset:34816
	ds_read_b128 v[210:213], v153 offset:35840
	ds_read_b128 v[214:217], v153 offset:36864
	ds_read_b128 v[218:221], v153 offset:37888
	ds_read_b128 v[222:225], v153 offset:38912
	ds_read_b128 v[226:229], v153 offset:39936
	global_load_lds_dwordx4 v[230:231], off
	v_lshl_add_u64 v[230:231], s[6:7], 0, v[132:133]
	s_mov_b32 m0, s55
	s_nop 0
	global_load_lds_dwordx4 v[230:231], off
	s_setprio 0
	s_waitcnt vmcnt(8)
	s_waitcnt lgkmcnt(0)
	s_barrier
	s_setprio 1
	v_mfma_f32_16x16x32_bf16 v[126:129], v[140:143], v[198:201], v[126:129]
	v_mfma_f32_16x16x32_bf16 v[122:125], v[162:165], v[198:201], v[122:125]
	v_mfma_f32_16x16x32_bf16 v[110:113], v[140:143], v[206:209], v[110:113]
	v_mfma_f32_16x16x32_bf16 v[106:109], v[162:165], v[206:209], v[106:109]
	v_mfma_f32_16x16x32_bf16 v[92:95], v[140:143], v[214:217], v[92:95]
	v_mfma_f32_16x16x32_bf16 v[88:91], v[162:165], v[214:217], v[88:91]
	v_mfma_f32_16x16x32_bf16 v[76:79], v[140:143], v[222:225], v[76:79]
	v_mfma_f32_16x16x32_bf16 v[72:75], v[162:165], v[222:225], v[72:75]
	v_mfma_f32_16x16x32_bf16 v[126:129], v[144:147], v[202:205], v[126:129]
	v_mfma_f32_16x16x32_bf16 v[122:125], v[166:169], v[202:205], v[122:125]
	v_mfma_f32_16x16x32_bf16 v[110:113], v[144:147], v[210:213], v[110:113]
	v_mfma_f32_16x16x32_bf16 v[106:109], v[166:169], v[210:213], v[106:109]
	v_mfma_f32_16x16x32_bf16 v[92:95], v[144:147], v[218:221], v[92:95]
	v_mfma_f32_16x16x32_bf16 v[88:91], v[166:169], v[218:221], v[88:91]
	v_mfma_f32_16x16x32_bf16 v[76:79], v[144:147], v[226:229], v[76:79]
	v_mfma_f32_16x16x32_bf16 v[72:75], v[166:169], v[226:229], v[72:75]
	s_setprio 0
	s_setprio 1
	v_mfma_f32_16x16x32_bf16 v[118:121], v[170:173], v[198:201], v[118:121]
	v_mfma_f32_16x16x32_bf16 v[114:117], v[190:193], v[198:201], v[114:117]
	v_mfma_f32_16x16x32_bf16 v[102:105], v[170:173], v[206:209], v[102:105]
	v_mfma_f32_16x16x32_bf16 v[98:101], v[190:193], v[206:209], v[98:101]
	v_mfma_f32_16x16x32_bf16 v[84:87], v[170:173], v[214:217], v[84:87]
	v_mfma_f32_16x16x32_bf16 v[80:83], v[190:193], v[214:217], v[80:83]
	v_mfma_f32_16x16x32_bf16 v[68:71], v[170:173], v[222:225], v[68:71]
	v_mfma_f32_16x16x32_bf16 v[64:67], v[190:193], v[222:225], v[64:67]
	v_mfma_f32_16x16x32_bf16 v[118:121], v[186:189], v[202:205], v[118:121]
	v_mfma_f32_16x16x32_bf16 v[114:117], v[194:197], v[202:205], v[114:117]
	v_mfma_f32_16x16x32_bf16 v[102:105], v[186:189], v[210:213], v[102:105]
	v_mfma_f32_16x16x32_bf16 v[98:101], v[194:197], v[210:213], v[98:101]
	v_mfma_f32_16x16x32_bf16 v[84:87], v[186:189], v[218:221], v[84:87]
	v_mfma_f32_16x16x32_bf16 v[80:83], v[194:197], v[218:221], v[80:83]
	v_mfma_f32_16x16x32_bf16 v[68:71], v[186:189], v[226:229], v[68:71]
	v_mfma_f32_16x16x32_bf16 v[64:67], v[194:197], v[226:229], v[64:67]
	s_setprio 0
	s_barrier
	s_setprio 2
	s_add_i32 s6, s67, s51
	v_lshl_add_u64 v[148:149], v[148:149], 0, s[16:17]
	s_mov_b32 m0, s6
	ds_read_b128 v[198:201], v153 offset:49152
	ds_read_b128 v[202:205], v153 offset:50176
	ds_read_b128 v[206:209], v153 offset:51200
	ds_read_b128 v[210:213], v153 offset:52224
	ds_read_b128 v[214:217], v153 offset:53248
	ds_read_b128 v[218:221], v153 offset:54272
	ds_read_b128 v[222:225], v153 offset:55296
	ds_read_b128 v[226:229], v153 offset:56320
	global_load_lds_dwordx4 v[148:149], off
	v_lshl_add_u64 v[148:149], v[154:155], 0, s[16:17]
	s_add_i32 m0, s6, 0x2000
	s_add_i32 s6, s68, s51
	global_load_lds_dwordx4 v[148:149], off
	v_lshl_add_u64 v[148:149], v[156:157], 0, s[16:17]
	s_mov_b32 m0, s6
	s_nop 0
	global_load_lds_dwordx4 v[148:149], off
	v_lshl_add_u64 v[148:149], v[158:159], 0, s[16:17]
	s_add_i32 m0, s6, 0x2000
	s_nop 0
	global_load_lds_dwordx4 v[148:149], off
	v_lshl_add_u64 v[148:149], v[182:183], 0, s[16:17]
	s_mov_b32 m0, s56
	s_nop 0
	global_load_lds_dwordx4 v[148:149], off
	v_lshl_add_u64 v[148:149], v[184:185], 0, s[16:17]
	s_mov_b32 m0, s57
	s_nop 0
	global_load_lds_dwordx4 v[148:149], off
	s_setprio 0
	s_waitcnt vmcnt(8)
	s_waitcnt lgkmcnt(0)
	s_barrier
	s_setprio 1
	v_mfma_f32_16x16x32_bf16 v[60:63], v[140:143], v[198:201], v[60:63]
	v_mfma_f32_16x16x32_bf16 v[56:59], v[162:165], v[198:201], v[56:59]
	v_mfma_f32_16x16x32_bf16 v[44:47], v[140:143], v[206:209], v[44:47]
	v_mfma_f32_16x16x32_bf16 v[40:43], v[162:165], v[206:209], v[40:43]
	v_mfma_f32_16x16x32_bf16 v[28:31], v[140:143], v[214:217], v[28:31]
	v_mfma_f32_16x16x32_bf16 v[24:27], v[162:165], v[214:217], v[24:27]
	v_mfma_f32_16x16x32_bf16 v[12:15], v[140:143], v[222:225], v[12:15]
	v_mfma_f32_16x16x32_bf16 v[8:11], v[162:165], v[222:225], v[8:11]
	v_mfma_f32_16x16x32_bf16 v[60:63], v[144:147], v[202:205], v[60:63]
	v_mfma_f32_16x16x32_bf16 v[56:59], v[166:169], v[202:205], v[56:59]
	v_mfma_f32_16x16x32_bf16 v[44:47], v[144:147], v[210:213], v[44:47]
	v_mfma_f32_16x16x32_bf16 v[40:43], v[166:169], v[210:213], v[40:43]
	v_mfma_f32_16x16x32_bf16 v[28:31], v[144:147], v[218:221], v[28:31]
	v_mfma_f32_16x16x32_bf16 v[24:27], v[166:169], v[218:221], v[24:27]
	v_mfma_f32_16x16x32_bf16 v[12:15], v[144:147], v[226:229], v[12:15]
	v_mfma_f32_16x16x32_bf16 v[8:11], v[166:169], v[226:229], v[8:11]
	s_setprio 0
	s_setprio 1
	v_mfma_f32_16x16x32_bf16 v[52:55], v[170:173], v[198:201], v[52:55]
	v_mfma_f32_16x16x32_bf16 v[48:51], v[190:193], v[198:201], v[48:51]
	v_mfma_f32_16x16x32_bf16 v[36:39], v[170:173], v[206:209], v[36:39]
	v_mfma_f32_16x16x32_bf16 v[32:35], v[190:193], v[206:209], v[32:35]
	v_mfma_f32_16x16x32_bf16 v[20:23], v[170:173], v[214:217], v[20:23]
	v_mfma_f32_16x16x32_bf16 v[16:19], v[190:193], v[214:217], v[16:19]
	v_mfma_f32_16x16x32_bf16 v[4:7], v[170:173], v[222:225], v[4:7]
	v_mfma_f32_16x16x32_bf16 v[0:3], v[190:193], v[222:225], v[0:3]
	v_mfma_f32_16x16x32_bf16 v[52:55], v[186:189], v[202:205], v[52:55]
	v_mfma_f32_16x16x32_bf16 v[48:51], v[194:197], v[202:205], v[48:51]
	v_mfma_f32_16x16x32_bf16 v[36:39], v[186:189], v[210:213], v[36:39]
	v_mfma_f32_16x16x32_bf16 v[32:35], v[194:197], v[210:213], v[32:35]
	v_mfma_f32_16x16x32_bf16 v[20:23], v[186:189], v[218:221], v[20:23]
	v_mfma_f32_16x16x32_bf16 v[16:19], v[194:197], v[218:221], v[16:19]
	v_mfma_f32_16x16x32_bf16 v[4:7], v[186:189], v[226:229], v[4:7]
	v_mfma_f32_16x16x32_bf16 v[0:3], v[194:197], v[226:229], v[0:3]
	s_add_u32 s4, s4, 0x100
	s_addc_u32 s5, s5, 0
	s_add_u32 s14, s14, 0x100
	s_addc_u32 s15, s15, 0
	s_setprio 0
	s_barrier
	s_setprio 2
	s_cmp_ge_u32 s66, s59
	s_mov_b32 s6, s66
	s_cbranch_scc0 .LBB0_490
	s_and_b64 vcc, exec, s[36:37]
	s_cbranch_vccz .LBB0_493
	s_barrier
